# GEMM K-loop LDS-DMA loads use SGPR-base plus 32-bit VGPR offset addressing (no per-load 64-bit VALU adds), on top of MFMA order and scan prio
# speedup vs baseline: 1.0091x; 1.0030x over previous
; #define PG8_STAGE(bufoff, gbase, voff) do { _Pragma("unroll") for (int _i = 0; _i < 2; ++_i) \
;         __builtin_amdgcn_global_load_lds((const unsigned*)((const char*)(gbase) + (voff)[_i]), (PG8_LAS unsigned*)(lds + (bufoff) + ldsw + _i * 8192), 16, 0, 0); } while (0)
; #define PG8_LDA(dst, b, h) do { _Pragma("unroll") for (int m = 0; m < 4; ++m) _Pragma("unroll") for (int k = 0; k < 2; ++k) dst[m][k] = *(const PG8_LAS bf16x8*)(lds + PG8_SA(b, h) + aoff + m * 2048 + k * 1024); } while (0)
; #define PG8_LDB(dst, b, h) do { _Pragma("unroll") for (int n = 0; n < 2; ++n) _Pragma("unroll") for (int k = 0; k < 2; ++k) dst[n][k] = *(const PG8_LAS bf16x8*)(lds + PG8_SB(b, h) + boff + n * 2048 + k * 1024); } while (0)
; #define PG8_MMA(ai, bj, At, Bt) do { __builtin_amdgcn_s_setprio(1); _Pragma("unroll") for (int m = 0; m < 4; ++m) _Pragma("unroll") for (int n = 0; n < 2; ++n) _Pragma("unroll") for (int k = 0; k < 2; ++k) \
;         acc[ai][bj][m][n] = __builtin_amdgcn_mfma_f32_16x16x32_bf16(Bt[n][k], At[m][k], acc[ai][bj][m][n], 0, 0, 0); __builtin_amdgcn_s_setprio(0); } while (0)
; #define PG8_WAIT_V(n) asm volatile("s_waitcnt vmcnt(" #n ")" ::: "memory")
; template <class Epi, class Sched, bool ALIGN_EPI = false, bool SP2 = false>
; __device__ __forceinline__ void gemm_phase(PG8_LAS unsigned char* lds, const Gemm g, const Sched& S, const Epi& E) {
;     ...
;             PG8_LDB(B0, 0, 0); PG8_LDB(B1, 0, 1); PG8_SCHED; PG8_LDA(At, 0, 0); PG8_STAGE(PG8_SA(1, 1), a1 + hstepA, voffA);
;             PG8_WAIT_V(8); PG8_WAIT_L(0); PG8_BAR; PG8_MMA(0, 0, At, B0); PG8_MMA(0, 1, At, B1); PG8_BAR; PG8_SCHED;
;             PG8_LDA(At, 0, 1); PG8_STAGE(PG8_SB(0, 0), b2, voffB); PG8_STAGE(PG8_SB(0, 1), b2 + hstepB, voffB); PG8_STAGE(PG8_SA(0, 0), a2, voffA);
;             PG8_WAIT_V(8); PG8_WAIT_L(0); PG8_BAR; PG8_MMA(1, 0, At, B0); PG8_MMA(1, 1, At, B1); PG8_BAR; PG8_SCHED;
;             PG8_LDB(B0, 1, 0); PG8_LDB(B1, 1, 1); PG8_SCHED; PG8_LDA(At, 1, 0); PG8_STAGE(PG8_SA(0, 1), a2 + hstepA, voffA);
;             PG8_WAIT_V(8); PG8_WAIT_L(0); PG8_BAR; PG8_MMA(0, 0, At, B0); PG8_MMA(0, 1, At, B1); PG8_BAR; PG8_SCHED;
;             PG8_LDA(At, 1, 1); PG8_STAGE(PG8_SB(1, 0), b3, voffB); PG8_STAGE(PG8_SB(1, 1), b3 + hstepB, voffB); PG8_STAGE(PG8_SA(1, 0), a3, voffA);
;             PG8_WAIT_V(8); PG8_WAIT_L(0); PG8_BAR; PG8_MMA(1, 0, At, B0); PG8_MMA(1, 1, At, B1); PG8_BAR; PG8_SCHED;
.LBB0_79:
	ds_read_b128 v[152:155], v148
	ds_read_b128 v[156:159], v148 offset:1024
	ds_read_b128 v[160:163], v148 offset:2048
	ds_read_b128 v[168:171], v148 offset:3072
	ds_read_b128 v[172:175], v149
	ds_read_b128 v[176:179], v149 offset:1024
	ds_read_b128 v[180:183], v149 offset:2048
	ds_read_b128 v[184:187], v149 offset:3072
	s_add_u32 s24, s22, 0xfff00080
	s_addc_u32 s25, s23, -1
	s_cmp_eq_u32 s64, 60
	s_cselect_b32 s27, s17, s25
	s_cselect_b32 s26, s60, s24
	s_cselect_b32 s25, s15, s63
	s_cselect_b32 s24, s61, s62
	s_add_u32 s98, s24, 0x80
	s_addc_u32 s99, s25, 0
	s_add_u32 s100, s26, 0x80
	s_addc_u32 s101, s27, 0
	s_add_i32 m0, s13, 0xc000
	ds_read_b128 v[188:191], v150
	ds_read_b128 v[192:195], v150 offset:1024
	ds_read_b128 v[196:199], v150 offset:2048
	ds_read_b128 v[200:203], v150 offset:3072
	ds_read_b128 v[204:207], v150 offset:4096
	ds_read_b128 v[208:211], v150 offset:5120
	ds_read_b128 v[212:215], v150 offset:6144
	ds_read_b128 v[216:219], v150 offset:7168
	global_load_lds_dwordx4 v138, s[22:23]
	s_add_i32 m0, s13, 0xe000
	s_nop 0
	global_load_lds_dwordx4 v140, s[22:23]
	s_waitcnt vmcnt(8)
	s_waitcnt lgkmcnt(0)
	s_barrier
	s_setprio 1
	s_waitcnt lgkmcnt(0)
	v_mfma_f32_16x16x32_bf16 v[126:129], v[152:155], v[188:191], v[126:129]
	v_mfma_f32_16x16x32_bf16 v[126:129], v[156:159], v[192:195], v[126:129]
	v_mfma_f32_16x16x32_bf16 v[122:125], v[168:171], v[192:195], v[122:125]
	v_mfma_f32_16x16x32_bf16 v[122:125], v[160:163], v[188:191], v[122:125]
	v_mfma_f32_16x16x32_bf16 v[114:117], v[160:163], v[196:199], v[114:117]
	v_mfma_f32_16x16x32_bf16 v[114:117], v[168:171], v[200:203], v[114:117]
	v_mfma_f32_16x16x32_bf16 v[118:121], v[156:159], v[200:203], v[118:121]
	v_mfma_f32_16x16x32_bf16 v[118:121], v[152:155], v[196:199], v[118:121]
	v_mfma_f32_16x16x32_bf16 v[102:105], v[152:155], v[204:207], v[102:105]
	v_mfma_f32_16x16x32_bf16 v[102:105], v[156:159], v[208:211], v[102:105]
	v_mfma_f32_16x16x32_bf16 v[98:101], v[168:171], v[208:211], v[98:101]
	v_mfma_f32_16x16x32_bf16 v[98:101], v[160:163], v[204:207], v[98:101]
	v_mfma_f32_16x16x32_bf16 v[82:85], v[160:163], v[212:215], v[82:85]
	v_mfma_f32_16x16x32_bf16 v[82:85], v[168:171], v[216:219], v[82:85]
	v_mfma_f32_16x16x32_bf16 v[86:89], v[156:159], v[216:219], v[86:89]
	v_mfma_f32_16x16x32_bf16 v[86:89], v[152:155], v[212:215], v[86:89]
	s_setprio 0
	s_setprio 1
	v_mfma_f32_16x16x32_bf16 v[110:113], v[172:175], v[188:191], v[110:113]
	v_mfma_f32_16x16x32_bf16 v[110:113], v[176:179], v[192:195], v[110:113]
	v_mfma_f32_16x16x32_bf16 v[106:109], v[184:187], v[192:195], v[106:109]
	v_mfma_f32_16x16x32_bf16 v[106:109], v[180:183], v[188:191], v[106:109]
	v_mfma_f32_16x16x32_bf16 v[90:93], v[180:183], v[196:199], v[90:93]
	v_mfma_f32_16x16x32_bf16 v[90:93], v[184:187], v[200:203], v[90:93]
	v_mfma_f32_16x16x32_bf16 v[94:97], v[176:179], v[200:203], v[94:97]
	v_mfma_f32_16x16x32_bf16 v[94:97], v[172:175], v[196:199], v[94:97]
	v_mfma_f32_16x16x32_bf16 v[78:81], v[172:175], v[204:207], v[78:81]
	v_mfma_f32_16x16x32_bf16 v[78:81], v[176:179], v[208:211], v[78:81]
	v_mfma_f32_16x16x32_bf16 v[74:77], v[184:187], v[208:211], v[74:77]
	v_mfma_f32_16x16x32_bf16 v[74:77], v[180:183], v[204:207], v[74:77]
	v_mfma_f32_16x16x32_bf16 v[66:69], v[180:183], v[212:215], v[66:69]
	v_mfma_f32_16x16x32_bf16 v[66:69], v[184:187], v[216:219], v[66:69]
	v_mfma_f32_16x16x32_bf16 v[70:73], v[176:179], v[216:219], v[70:73]
	v_mfma_f32_16x16x32_bf16 v[70:73], v[172:175], v[212:215], v[70:73]
	s_setprio 0
	s_barrier
	s_add_i32 s65, s38, s3
	s_mov_b32 m0, s65
	ds_read_b128 v[188:191], v150 offset:16384
	ds_read_b128 v[192:195], v150 offset:17408
	ds_read_b128 v[196:199], v150 offset:18432
	ds_read_b128 v[200:203], v150 offset:19456
	ds_read_b128 v[204:207], v150 offset:20480
	ds_read_b128 v[208:211], v150 offset:21504
	ds_read_b128 v[212:215], v150 offset:22528
	ds_read_b128 v[216:219], v150 offset:23552
	global_load_lds_dwordx4 v134, s[24:25]
	s_add_i32 m0, s65, 0x2000
	s_add_u32 s66, s24, 0x100000
	s_addc_u32 s67, s25, 0
	s_add_i32 s65, s39, s3
	global_load_lds_dwordx4 v130, s[24:25]
	s_mov_b32 m0, s65
	s_nop 0
	global_load_lds_dwordx4 v134, s[66:67]
	s_add_i32 m0, s65, 0x2000
	s_nop 0
	global_load_lds_dwordx4 v130, s[66:67]
	s_mov_b32 m0, s13
	s_nop 0
	global_load_lds_dwordx4 v136, s[26:27]
	s_mov_b32 m0, s30
	s_nop 0
	global_load_lds_dwordx4 v132, s[26:27]
	s_waitcnt vmcnt(8)
	s_waitcnt lgkmcnt(0)
	s_barrier
	s_setprio 1
	s_waitcnt lgkmcnt(0)
	v_mfma_f32_16x16x32_bf16 v[62:65], v[152:155], v[188:191], v[62:65]
	v_mfma_f32_16x16x32_bf16 v[62:65], v[156:159], v[192:195], v[62:65]
	v_mfma_f32_16x16x32_bf16 v[58:61], v[168:171], v[192:195], v[58:61]
	v_mfma_f32_16x16x32_bf16 v[58:61], v[160:163], v[188:191], v[58:61]
	v_mfma_f32_16x16x32_bf16 v[50:53], v[160:163], v[196:199], v[50:53]
	v_mfma_f32_16x16x32_bf16 v[50:53], v[168:171], v[200:203], v[50:53]
	v_mfma_f32_16x16x32_bf16 v[54:57], v[156:159], v[200:203], v[54:57]
	v_mfma_f32_16x16x32_bf16 v[54:57], v[152:155], v[196:199], v[54:57]
	v_mfma_f32_16x16x32_bf16 v[38:41], v[152:155], v[204:207], v[38:41]
	v_mfma_f32_16x16x32_bf16 v[38:41], v[156:159], v[208:211], v[38:41]
	v_mfma_f32_16x16x32_bf16 v[34:37], v[168:171], v[208:211], v[34:37]
	v_mfma_f32_16x16x32_bf16 v[34:37], v[160:163], v[204:207], v[34:37]
	v_mfma_f32_16x16x32_bf16 v[18:21], v[160:163], v[212:215], v[18:21]
	v_mfma_f32_16x16x32_bf16 v[18:21], v[168:171], v[216:219], v[18:21]
	v_mfma_f32_16x16x32_bf16 v[22:25], v[156:159], v[216:219], v[22:25]
	v_mfma_f32_16x16x32_bf16 v[22:25], v[152:155], v[212:215], v[22:25]
	s_setprio 0
	s_setprio 1
	v_mfma_f32_16x16x32_bf16 v[46:49], v[172:175], v[188:191], v[46:49]
	v_mfma_f32_16x16x32_bf16 v[46:49], v[176:179], v[192:195], v[46:49]
	v_mfma_f32_16x16x32_bf16 v[42:45], v[184:187], v[192:195], v[42:45]
	v_mfma_f32_16x16x32_bf16 v[42:45], v[180:183], v[188:191], v[42:45]
	v_mfma_f32_16x16x32_bf16 v[26:29], v[180:183], v[196:199], v[26:29]
	v_mfma_f32_16x16x32_bf16 v[26:29], v[184:187], v[200:203], v[26:29]
	v_mfma_f32_16x16x32_bf16 v[30:33], v[176:179], v[200:203], v[30:33]
	v_mfma_f32_16x16x32_bf16 v[30:33], v[172:175], v[196:199], v[30:33]
	v_mfma_f32_16x16x32_bf16 v[14:17], v[172:175], v[204:207], v[14:17]
	v_mfma_f32_16x16x32_bf16 v[14:17], v[176:179], v[208:211], v[14:17]
	v_mfma_f32_16x16x32_bf16 v[10:13], v[184:187], v[208:211], v[10:13]
	v_mfma_f32_16x16x32_bf16 v[10:13], v[180:183], v[204:207], v[10:13]
	v_mfma_f32_16x16x32_bf16 v[2:5], v[180:183], v[212:215], v[2:5]
	v_mfma_f32_16x16x32_bf16 v[2:5], v[184:187], v[216:219], v[2:5]
	v_mfma_f32_16x16x32_bf16 v[6:9], v[176:179], v[216:219], v[6:9]
	v_mfma_f32_16x16x32_bf16 v[6:9], v[172:175], v[212:215], v[6:9]
	s_setprio 0
	s_barrier
; #define PG8_STAGE(bufoff, gbase, voff) do { _Pragma("unroll") for (int _i = 0; _i < 2; ++_i) \
;         __builtin_amdgcn_global_load_lds((const unsigned*)((const char*)(gbase) + (voff)[_i]), (PG8_LAS unsigned*)(lds + (bufoff) + ldsw + _i * 8192), 16, 0, 0); } while (0)
; #define PG8_LDA(dst, b, h) do { _Pragma("unroll") for (int m = 0; m < 4; ++m) _Pragma("unroll") for (int k = 0; k < 2; ++k) dst[m][k] = *(const PG8_LAS bf16x8*)(lds + PG8_SA(b, h) + aoff + m * 2048 + k * 1024); } while (0)
; #define PG8_LDB(dst, b, h) do { _Pragma("unroll") for (int n = 0; n < 2; ++n) _Pragma("unroll") for (int k = 0; k < 2; ++k) dst[n][k] = *(const PG8_LAS bf16x8*)(lds + PG8_SB(b, h) + boff + n * 2048 + k * 1024); } while (0)
; #define PG8_MMA(ai, bj, At, Bt) do { __builtin_amdgcn_s_setprio(1); _Pragma("unroll") for (int m = 0; m < 4; ++m) _Pragma("unroll") for (int n = 0; n < 2; ++n) _Pragma("unroll") for (int k = 0; k < 2; ++k) \
;         acc[ai][bj][m][n] = __builtin_amdgcn_mfma_f32_16x16x32_bf16(Bt[n][k], At[m][k], acc[ai][bj][m][n], 0, 0, 0); __builtin_amdgcn_s_setprio(0); } while (0)
; #define PG8_WAIT_V(n) asm volatile("s_waitcnt vmcnt(" #n ")" ::: "memory")
; template <class Epi, class Sched, bool ALIGN_EPI = false, bool SP2 = false>
; __device__ __forceinline__ void gemm_phase(PG8_LAS unsigned char* lds, const Gemm g, const Sched& S, const Epi& E) {
;     ...
;             PG8_LDB(B0, 0, 0); PG8_LDB(B1, 0, 1); PG8_SCHED; PG8_LDA(At, 0, 0); PG8_STAGE(PG8_SA(1, 1), a1 + hstepA, voffA);
;             PG8_WAIT_V(8); PG8_WAIT_L(0); PG8_BAR; PG8_MMA(0, 0, At, B0); PG8_MMA(0, 1, At, B1); PG8_BAR; PG8_SCHED;
;             PG8_LDA(At, 0, 1); PG8_STAGE(PG8_SB(0, 0), b2, voffB); PG8_STAGE(PG8_SB(0, 1), b2 + hstepB, voffB); PG8_STAGE(PG8_SA(0, 0), a2, voffA);
;             PG8_WAIT_V(8); PG8_WAIT_L(0); PG8_BAR; PG8_MMA(1, 0, At, B0); PG8_MMA(1, 1, At, B1); PG8_BAR; PG8_SCHED;
;             PG8_LDB(B0, 1, 0); PG8_LDB(B1, 1, 1); PG8_SCHED; PG8_LDA(At, 1, 0); PG8_STAGE(PG8_SA(0, 1), a2 + hstepA, voffA);
;             PG8_WAIT_V(8); PG8_WAIT_L(0); PG8_BAR; PG8_MMA(0, 0, At, B0); PG8_MMA(0, 1, At, B1); PG8_BAR; PG8_SCHED;
;             PG8_LDA(At, 1, 1); PG8_STAGE(PG8_SB(1, 0), b3, voffB); PG8_STAGE(PG8_SB(1, 1), b3 + hstepB, voffB); PG8_STAGE(PG8_SA(1, 0), a3, voffA);
;             PG8_WAIT_V(8); PG8_WAIT_L(0); PG8_BAR; PG8_MMA(1, 0, At, B0); PG8_MMA(1, 1, At, B1); PG8_BAR; PG8_SCHED;
	s_add_i32 s65, 0, 0x18000
	v_add_u32_e32 v151, s65, v146
	s_add_i32 s66, 0, 0x1c000
	ds_read_b128 v[152:155], v151
	ds_read_b128 v[156:159], v151 offset:1024
	ds_read_b128 v[160:163], v151 offset:2048
	ds_read_b128 v[168:171], v151 offset:3072
	v_add_u32_e32 v151, s66, v146
	ds_read_b128 v[172:175], v151
	ds_read_b128 v[176:179], v151 offset:1024
	ds_read_b128 v[180:183], v151 offset:2048
	ds_read_b128 v[184:187], v151 offset:3072
	s_add_u32 s26, s26, 0x100000
	s_addc_u32 s27, s27, 0
	s_mov_b32 m0, s31
	ds_read_b128 v[188:191], v150 offset:32768
	ds_read_b128 v[192:195], v150 offset:33792
	ds_read_b128 v[196:199], v150 offset:34816
	ds_read_b128 v[200:203], v150 offset:35840
	ds_read_b128 v[204:207], v150 offset:36864
	ds_read_b128 v[208:211], v150 offset:37888
	ds_read_b128 v[212:215], v150 offset:38912
	ds_read_b128 v[216:219], v150 offset:39936
	global_load_lds_dwordx4 v136, s[26:27]
	s_mov_b32 m0, s33
	s_nop 0
	global_load_lds_dwordx4 v132, s[26:27]
	s_waitcnt vmcnt(8)
	s_waitcnt lgkmcnt(0)
	s_barrier
	s_setprio 1
	s_waitcnt lgkmcnt(0)
	v_mfma_f32_16x16x32_bf16 v[126:129], v[152:155], v[188:191], v[126:129]
	v_mfma_f32_16x16x32_bf16 v[126:129], v[156:159], v[192:195], v[126:129]
	v_mfma_f32_16x16x32_bf16 v[122:125], v[168:171], v[192:195], v[122:125]
	v_mfma_f32_16x16x32_bf16 v[122:125], v[160:163], v[188:191], v[122:125]
	v_mfma_f32_16x16x32_bf16 v[114:117], v[160:163], v[196:199], v[114:117]
	v_mfma_f32_16x16x32_bf16 v[114:117], v[168:171], v[200:203], v[114:117]
	v_mfma_f32_16x16x32_bf16 v[118:121], v[156:159], v[200:203], v[118:121]
	v_mfma_f32_16x16x32_bf16 v[118:121], v[152:155], v[196:199], v[118:121]
	v_mfma_f32_16x16x32_bf16 v[102:105], v[152:155], v[204:207], v[102:105]
	v_mfma_f32_16x16x32_bf16 v[102:105], v[156:159], v[208:211], v[102:105]
	v_mfma_f32_16x16x32_bf16 v[98:101], v[168:171], v[208:211], v[98:101]
	v_mfma_f32_16x16x32_bf16 v[98:101], v[160:163], v[204:207], v[98:101]
	v_mfma_f32_16x16x32_bf16 v[82:85], v[160:163], v[212:215], v[82:85]
	v_mfma_f32_16x16x32_bf16 v[82:85], v[168:171], v[216:219], v[82:85]
	v_mfma_f32_16x16x32_bf16 v[86:89], v[156:159], v[216:219], v[86:89]
	v_mfma_f32_16x16x32_bf16 v[86:89], v[152:155], v[212:215], v[86:89]
	s_setprio 0
	s_setprio 1
	v_mfma_f32_16x16x32_bf16 v[110:113], v[172:175], v[188:191], v[110:113]
	v_mfma_f32_16x16x32_bf16 v[110:113], v[176:179], v[192:195], v[110:113]
	v_mfma_f32_16x16x32_bf16 v[106:109], v[184:187], v[192:195], v[106:109]
	v_mfma_f32_16x16x32_bf16 v[106:109], v[180:183], v[188:191], v[106:109]
	v_mfma_f32_16x16x32_bf16 v[90:93], v[180:183], v[196:199], v[90:93]
	v_mfma_f32_16x16x32_bf16 v[90:93], v[184:187], v[200:203], v[90:93]
	v_mfma_f32_16x16x32_bf16 v[94:97], v[176:179], v[200:203], v[94:97]
	v_mfma_f32_16x16x32_bf16 v[94:97], v[172:175], v[196:199], v[94:97]
	v_mfma_f32_16x16x32_bf16 v[78:81], v[172:175], v[204:207], v[78:81]
	v_mfma_f32_16x16x32_bf16 v[78:81], v[176:179], v[208:211], v[78:81]
	v_mfma_f32_16x16x32_bf16 v[74:77], v[184:187], v[208:211], v[74:77]
	v_mfma_f32_16x16x32_bf16 v[74:77], v[180:183], v[204:207], v[74:77]
	v_mfma_f32_16x16x32_bf16 v[66:69], v[180:183], v[212:215], v[66:69]
	v_mfma_f32_16x16x32_bf16 v[66:69], v[184:187], v[216:219], v[66:69]
	v_mfma_f32_16x16x32_bf16 v[70:73], v[176:179], v[216:219], v[70:73]
	v_mfma_f32_16x16x32_bf16 v[70:73], v[172:175], v[212:215], v[70:73]
	s_setprio 0
	s_barrier
	s_add_i32 s26, s65, s3
	s_mov_b32 m0, s26
	ds_read_b128 v[188:191], v150 offset:49152
	ds_read_b128 v[192:195], v150 offset:50176
	ds_read_b128 v[196:199], v150 offset:51200
	ds_read_b128 v[200:203], v150 offset:52224
	ds_read_b128 v[204:207], v150 offset:53248
	ds_read_b128 v[208:211], v150 offset:54272
	ds_read_b128 v[212:215], v150 offset:55296
	ds_read_b128 v[216:219], v150 offset:56320
	global_load_lds_dwordx4 v134, s[98:99]
	s_add_i32 m0, s26, 0x2000
	s_add_u32 s24, s24, 0x100080
	s_addc_u32 s25, s25, 0
	s_add_i32 s26, s66, s3
	global_load_lds_dwordx4 v130, s[98:99]
	s_mov_b32 m0, s26
	s_nop 0
	global_load_lds_dwordx4 v134, s[24:25]
	s_add_i32 m0, s26, 0x2000
	s_nop 0
	global_load_lds_dwordx4 v130, s[24:25]
	s_mov_b32 m0, s35
	s_nop 0
	global_load_lds_dwordx4 v136, s[100:101]
	s_mov_b32 m0, s36
	s_nop 0
	global_load_lds_dwordx4 v132, s[100:101]
	s_waitcnt vmcnt(8)
	s_waitcnt lgkmcnt(0)
	s_barrier
	s_setprio 1
	s_waitcnt lgkmcnt(0)
	v_mfma_f32_16x16x32_bf16 v[62:65], v[152:155], v[188:191], v[62:65]
	v_mfma_f32_16x16x32_bf16 v[62:65], v[156:159], v[192:195], v[62:65]
	v_mfma_f32_16x16x32_bf16 v[58:61], v[168:171], v[192:195], v[58:61]
	v_mfma_f32_16x16x32_bf16 v[58:61], v[160:163], v[188:191], v[58:61]
	v_mfma_f32_16x16x32_bf16 v[50:53], v[160:163], v[196:199], v[50:53]
	v_mfma_f32_16x16x32_bf16 v[50:53], v[168:171], v[200:203], v[50:53]
	v_mfma_f32_16x16x32_bf16 v[54:57], v[156:159], v[200:203], v[54:57]
	v_mfma_f32_16x16x32_bf16 v[54:57], v[152:155], v[196:199], v[54:57]
	v_mfma_f32_16x16x32_bf16 v[38:41], v[152:155], v[204:207], v[38:41]
	v_mfma_f32_16x16x32_bf16 v[38:41], v[156:159], v[208:211], v[38:41]
	v_mfma_f32_16x16x32_bf16 v[34:37], v[168:171], v[208:211], v[34:37]
	v_mfma_f32_16x16x32_bf16 v[34:37], v[160:163], v[204:207], v[34:37]
	v_mfma_f32_16x16x32_bf16 v[18:21], v[160:163], v[212:215], v[18:21]
	v_mfma_f32_16x16x32_bf16 v[18:21], v[168:171], v[216:219], v[18:21]
	v_mfma_f32_16x16x32_bf16 v[22:25], v[156:159], v[216:219], v[22:25]
	v_mfma_f32_16x16x32_bf16 v[22:25], v[152:155], v[212:215], v[22:25]
	s_setprio 0
	s_setprio 1
	v_mfma_f32_16x16x32_bf16 v[46:49], v[172:175], v[188:191], v[46:49]
	v_mfma_f32_16x16x32_bf16 v[46:49], v[176:179], v[192:195], v[46:49]
	v_mfma_f32_16x16x32_bf16 v[42:45], v[184:187], v[192:195], v[42:45]
	v_mfma_f32_16x16x32_bf16 v[42:45], v[180:183], v[188:191], v[42:45]
	v_mfma_f32_16x16x32_bf16 v[26:29], v[180:183], v[196:199], v[26:29]
	v_mfma_f32_16x16x32_bf16 v[26:29], v[184:187], v[200:203], v[26:29]
	v_mfma_f32_16x16x32_bf16 v[30:33], v[176:179], v[200:203], v[30:33]
	v_mfma_f32_16x16x32_bf16 v[30:33], v[172:175], v[196:199], v[30:33]
	v_mfma_f32_16x16x32_bf16 v[14:17], v[172:175], v[204:207], v[14:17]
	v_mfma_f32_16x16x32_bf16 v[14:17], v[176:179], v[208:211], v[14:17]
	v_mfma_f32_16x16x32_bf16 v[10:13], v[184:187], v[208:211], v[10:13]
	v_mfma_f32_16x16x32_bf16 v[10:13], v[180:183], v[204:207], v[10:13]
	v_mfma_f32_16x16x32_bf16 v[2:5], v[180:183], v[212:215], v[2:5]
	v_mfma_f32_16x16x32_bf16 v[2:5], v[184:187], v[216:219], v[2:5]
	v_mfma_f32_16x16x32_bf16 v[6:9], v[176:179], v[216:219], v[6:9]
	v_mfma_f32_16x16x32_bf16 v[6:9], v[172:175], v[212:215], v[6:9]
	s_setprio 0
	s_barrier
	s_add_i32 s64, s64, 2
	s_add_u32 s22, s22, 0x100
	s_addc_u32 s23, s23, 0
	s_add_u32 s62, s62, 0x100
	s_addc_u32 s63, s63, 0
	s_cmp_gt_u32 s64, 61
	s_cbranch_scc0 .LBB0_79
	s_and_b64 vcc, exec, s[10:11]
	s_cbranch_vccz .LBB0_82
	s_barrier

; #define PG8_STAGE(bufoff, gbase, voff) do { _Pragma("unroll") for (int _i = 0; _i < 2; ++_i) \
;         __builtin_amdgcn_global_load_lds((const unsigned*)((const char*)(gbase) + (voff)[_i]), (PG8_LAS unsigned*)(lds + (bufoff) + ldsw + _i * 8192), 16, 0, 0); } while (0)
; #define PG8_LDA(dst, b, h) do { _Pragma("unroll") for (int m = 0; m < 4; ++m) _Pragma("unroll") for (int k = 0; k < 2; ++k) dst[m][k] = *(const PG8_LAS bf16x8*)(lds + PG8_SA(b, h) + aoff + m * 2048 + k * 1024); } while (0)
; #define PG8_LDB(dst, b, h) do { _Pragma("unroll") for (int n = 0; n < 2; ++n) _Pragma("unroll") for (int k = 0; k < 2; ++k) dst[n][k] = *(const PG8_LAS bf16x8*)(lds + PG8_SB(b, h) + boff + n * 2048 + k * 1024); } while (0)
; #define PG8_MMA(ai, bj, At, Bt) do { __builtin_amdgcn_s_setprio(1); _Pragma("unroll") for (int m = 0; m < 4; ++m) _Pragma("unroll") for (int n = 0; n < 2; ++n) _Pragma("unroll") for (int k = 0; k < 2; ++k) \
;         acc[ai][bj][m][n] = __builtin_amdgcn_mfma_f32_16x16x32_bf16(Bt[n][k], At[m][k], acc[ai][bj][m][n], 0, 0, 0); __builtin_amdgcn_s_setprio(0); } while (0)
; #define PG8_WAIT_V(n) asm volatile("s_waitcnt vmcnt(" #n ")" ::: "memory")
; #define PG8_WAIT_L(n) asm volatile("s_waitcnt lgkmcnt(" #n ")" ::: "memory")
; #define PG8_BAR __builtin_amdgcn_s_barrier()
; template <class Epi, class Sched, bool ALIGN_EPI = false, bool SP2 = false>
; __device__ __forceinline__ void gemm_phase(PG8_LAS unsigned char* lds, const Gemm g, const Sched& S, const Epi& E) {
;     ...
;             const char* a1 = cA + (size_t)(t + 1) * kstep + (t >= g.kj_t ? g.kj_bytes : 0);
;             const char* a2 = last ? nA : cA + (size_t)(t + 2) * kstep + (t + 2 >= g.kj_t ? g.kj_bytes : 0); const char* b2 = last ? nB : cB + (size_t)(t + 2) * kstep;
;             const char* a3 = a2 + kstep; const char* b3 = b2 + kstep;
;             if (last && has_next) S.a_ready(nxt);
;             if constexpr (Epi::MIDK) { if (t == g.kj_t) E.midk(acc, cur, wr, fr); }
;             if constexpr (SP2) {
;             PG8_LDB(B0, 0, 0); PG8_LDB(B1, 0, 1); PG8_SCHED; PG8_LDA(At, 0, 0); PG8_STAGE(PG8_SA(1, 1), a1 + hstepA, voffA);
;             PG8_WAIT_V(8); PG8_WAIT_L(0); PG8_BAR; PG8_MMA(0, 0, At, B0); PG8_MMA(0, 1, At, B1); PG8_BAR; PG8_SCHED;
;             PG8_LDA(At, 0, 1); PG8_STAGE(PG8_SB(0, 0), b2, voffB); PG8_STAGE(PG8_SB(0, 1), b2 + hstepB, voffB); PG8_STAGE(PG8_SA(0, 0), a2, voffA);
.LBB0_436:
	s_cmp_lt_u32 s65, 64
	s_cselect_b32 s67, 0, 0x4000
	s_add_i32 s66, s65, 2
	s_cmp_lt_u32 s65, 62
	s_cselect_b32 s30, 0, 0x4000
	s_add_u32 s30, s30, s4
	v_add_u32_e32 v3, s53, v167
	s_addc_u32 s31, 0, s5
	ds_read_b128 v[140:143], v3
	ds_read_b128 v[144:147], v3 offset:1024
	ds_read_b128 v[148:151], v3 offset:2048
	ds_read_b128 v[152:155], v3 offset:3072
	v_add_u32_e32 v3, s60, v167
	s_add_u32 s30, s28, s30
	ds_read_b128 v[156:159], v3
	ds_read_b128 v[160:163], v3 offset:1024
	ds_read_b128 v[186:189], v3 offset:2048
	ds_read_b128 v[196:199], v3 offset:3072
	s_addc_u32 s31, s29, s31
	s_add_u32 s30, s30, 0x100
	s_addc_u32 s31, s31, 0
	s_add_u32 s68, s63, s4
	s_addc_u32 s69, s64, s5
	s_cmpk_eq_i32 s4, 0x3f00
	s_cselect_b32 s35, s23, s31
	s_cselect_b32 s34, s22, s30
	s_cselect_b32 s31, s21, s69
	s_cselect_b32 s30, s62, s68
	s_add_u32 s98, s30, 0x80
	s_addc_u32 s99, s31, 0
	s_add_u32 s100, s34, 0x80
	s_addc_u32 s101, s35, 0
	s_add_u32 s68, s67, s4
	s_addc_u32 s69, 0, s5
	s_add_u32 s68, s68, s28
	s_addc_u32 s69, s69, s29
	s_add_i32 m0, s27, 0xc000
	ds_read_b128 v[200:203], v194
	ds_read_b128 v[204:207], v194 offset:1024
	ds_read_b128 v[208:211], v194 offset:2048
	ds_read_b128 v[212:215], v194 offset:3072
	ds_read_b128 v[216:219], v194 offset:4096
	ds_read_b128 v[220:223], v194 offset:5120
	ds_read_b128 v[224:227], v194 offset:6144
	ds_read_b128 v[228:231], v194 offset:7168
	global_load_lds_dwordx4 v178, s[68:69]
	s_add_i32 m0, s27, 0xe000
	s_nop 0
	global_load_lds_dwordx4 v176, s[68:69]
	s_waitcnt vmcnt(8)
	s_waitcnt lgkmcnt(0)
	s_barrier
	s_setprio 1
	s_waitcnt lgkmcnt(0)
	v_mfma_f32_16x16x32_bf16 v[130:133], v[140:143], v[200:203], v[130:133]
	v_mfma_f32_16x16x32_bf16 v[130:133], v[144:147], v[204:207], v[130:133]
	v_mfma_f32_16x16x32_bf16 v[126:129], v[152:155], v[204:207], v[126:129]
	v_mfma_f32_16x16x32_bf16 v[126:129], v[148:151], v[200:203], v[126:129]
	v_mfma_f32_16x16x32_bf16 v[110:113], v[148:151], v[208:211], v[110:113]
	v_mfma_f32_16x16x32_bf16 v[110:113], v[152:155], v[212:215], v[110:113]
	v_mfma_f32_16x16x32_bf16 v[114:117], v[144:147], v[212:215], v[114:117]
	v_mfma_f32_16x16x32_bf16 v[114:117], v[140:143], v[208:211], v[114:117]
	v_mfma_f32_16x16x32_bf16 v[98:101], v[140:143], v[216:219], v[98:101]
	v_mfma_f32_16x16x32_bf16 v[98:101], v[144:147], v[220:223], v[98:101]
	v_mfma_f32_16x16x32_bf16 v[94:97], v[152:155], v[220:223], v[94:97]
	v_mfma_f32_16x16x32_bf16 v[94:97], v[148:151], v[216:219], v[94:97]
	v_mfma_f32_16x16x32_bf16 v[78:81], v[148:151], v[224:227], v[78:81]
	v_mfma_f32_16x16x32_bf16 v[78:81], v[152:155], v[228:231], v[78:81]
	v_mfma_f32_16x16x32_bf16 v[82:85], v[144:147], v[228:231], v[82:85]
	v_mfma_f32_16x16x32_bf16 v[82:85], v[140:143], v[224:227], v[82:85]
	s_setprio 0
	s_setprio 1
	v_mfma_f32_16x16x32_bf16 v[122:125], v[156:159], v[200:203], v[122:125]
	v_mfma_f32_16x16x32_bf16 v[122:125], v[160:163], v[204:207], v[122:125]
	v_mfma_f32_16x16x32_bf16 v[118:121], v[196:199], v[204:207], v[118:121]
	v_mfma_f32_16x16x32_bf16 v[118:121], v[186:189], v[200:203], v[118:121]
	v_mfma_f32_16x16x32_bf16 v[102:105], v[186:189], v[208:211], v[102:105]
	v_mfma_f32_16x16x32_bf16 v[102:105], v[196:199], v[212:215], v[102:105]
	v_mfma_f32_16x16x32_bf16 v[106:109], v[160:163], v[212:215], v[106:109]
	v_mfma_f32_16x16x32_bf16 v[106:109], v[156:159], v[208:211], v[106:109]
	v_mfma_f32_16x16x32_bf16 v[90:93], v[156:159], v[216:219], v[90:93]
	v_mfma_f32_16x16x32_bf16 v[90:93], v[160:163], v[220:223], v[90:93]
	v_mfma_f32_16x16x32_bf16 v[86:89], v[196:199], v[220:223], v[86:89]
	v_mfma_f32_16x16x32_bf16 v[86:89], v[186:189], v[216:219], v[86:89]
	v_mfma_f32_16x16x32_bf16 v[70:73], v[186:189], v[224:227], v[70:73]
	v_mfma_f32_16x16x32_bf16 v[70:73], v[196:199], v[228:231], v[70:73]
	v_mfma_f32_16x16x32_bf16 v[74:77], v[160:163], v[228:231], v[74:77]
	v_mfma_f32_16x16x32_bf16 v[74:77], v[156:159], v[224:227], v[74:77]
	s_setprio 0
	s_barrier
	s_add_i32 s67, s53, s36
	s_mov_b32 m0, s67
	ds_read_b128 v[200:203], v194 offset:16384
	ds_read_b128 v[204:207], v194 offset:17408
	ds_read_b128 v[208:211], v194 offset:18432
	ds_read_b128 v[212:215], v194 offset:19456
	ds_read_b128 v[216:219], v194 offset:20480
	ds_read_b128 v[220:223], v194 offset:21504
	ds_read_b128 v[224:227], v194 offset:22528
	ds_read_b128 v[228:231], v194 offset:23552
	global_load_lds_dwordx4 v170, s[30:31]
	s_add_i32 m0, s67, 0x2000
	s_add_u32 s68, s30, 0x200000
	s_addc_u32 s69, s31, 0
	s_add_i32 s67, s60, s36
	global_load_lds_dwordx4 v174, s[30:31]
	s_mov_b32 m0, s67
	s_nop 0
	global_load_lds_dwordx4 v170, s[68:69]
	s_add_i32 m0, s67, 0x2000
	s_nop 0
	global_load_lds_dwordx4 v174, s[68:69]
	s_mov_b32 m0, s27
	s_nop 0
	global_load_lds_dwordx4 v168, s[34:35]
	s_mov_b32 m0, s37
	s_nop 0
	global_load_lds_dwordx4 v172, s[34:35]
	s_waitcnt vmcnt(8)
	s_waitcnt lgkmcnt(0)
	s_barrier
; #define PG8_STAGE(bufoff, gbase, voff) do { _Pragma("unroll") for (int _i = 0; _i < 2; ++_i) \
;         __builtin_amdgcn_global_load_lds((const unsigned*)((const char*)(gbase) + (voff)[_i]), (PG8_LAS unsigned*)(lds + (bufoff) + ldsw + _i * 8192), 16, 0, 0); } while (0)
; #define PG8_LDA(dst, b, h) do { _Pragma("unroll") for (int m = 0; m < 4; ++m) _Pragma("unroll") for (int k = 0; k < 2; ++k) dst[m][k] = *(const PG8_LAS bf16x8*)(lds + PG8_SA(b, h) + aoff + m * 2048 + k * 1024); } while (0)
; #define PG8_LDB(dst, b, h) do { _Pragma("unroll") for (int n = 0; n < 2; ++n) _Pragma("unroll") for (int k = 0; k < 2; ++k) dst[n][k] = *(const PG8_LAS bf16x8*)(lds + PG8_SB(b, h) + boff + n * 2048 + k * 1024); } while (0)
; #define PG8_MMA(ai, bj, At, Bt) do { __builtin_amdgcn_s_setprio(1); _Pragma("unroll") for (int m = 0; m < 4; ++m) _Pragma("unroll") for (int n = 0; n < 2; ++n) _Pragma("unroll") for (int k = 0; k < 2; ++k) \
;         acc[ai][bj][m][n] = __builtin_amdgcn_mfma_f32_16x16x32_bf16(Bt[n][k], At[m][k], acc[ai][bj][m][n], 0, 0, 0); __builtin_amdgcn_s_setprio(0); } while (0)
; #define PG8_WAIT_V(n) asm volatile("s_waitcnt vmcnt(" #n ")" ::: "memory")
; #define PG8_WAIT_L(n) asm volatile("s_waitcnt lgkmcnt(" #n ")" ::: "memory")
; #define PG8_BAR __builtin_amdgcn_s_barrier()
; #define PG8_SCHED __builtin_amdgcn_sched_barrier(0)
; template <class Epi, class Sched, bool ALIGN_EPI = false, bool SP2 = false>
; __device__ __forceinline__ void gemm_phase(PG8_LAS unsigned char* lds, const Gemm g, const Sched& S, const Epi& E) {
;     ...
;             PG8_WAIT_V(8); PG8_WAIT_L(0); PG8_BAR; PG8_MMA(1, 0, At, B0); PG8_MMA(1, 1, At, B1); PG8_BAR; PG8_SCHED;
;             PG8_LDB(B0, 1, 0); PG8_LDB(B1, 1, 1); PG8_SCHED; PG8_LDA(At, 1, 0); PG8_STAGE(PG8_SA(0, 1), a2 + hstepA, voffA);
;             PG8_WAIT_V(8); PG8_WAIT_L(0); PG8_BAR; PG8_MMA(0, 0, At, B0); PG8_MMA(0, 1, At, B1); PG8_BAR; PG8_SCHED;
	s_setprio 1
	s_waitcnt lgkmcnt(0)
	v_mfma_f32_16x16x32_bf16 v[66:69], v[140:143], v[200:203], v[66:69]
	v_mfma_f32_16x16x32_bf16 v[66:69], v[144:147], v[204:207], v[66:69]
	v_mfma_f32_16x16x32_bf16 v[62:65], v[152:155], v[204:207], v[62:65]
	v_mfma_f32_16x16x32_bf16 v[62:65], v[148:151], v[200:203], v[62:65]
	v_mfma_f32_16x16x32_bf16 v[46:49], v[148:151], v[208:211], v[46:49]
	v_mfma_f32_16x16x32_bf16 v[46:49], v[152:155], v[212:215], v[46:49]
	v_mfma_f32_16x16x32_bf16 v[50:53], v[144:147], v[212:215], v[50:53]
	v_mfma_f32_16x16x32_bf16 v[50:53], v[140:143], v[208:211], v[50:53]
	v_mfma_f32_16x16x32_bf16 v[34:37], v[140:143], v[216:219], v[34:37]
	v_mfma_f32_16x16x32_bf16 v[34:37], v[144:147], v[220:223], v[34:37]
	v_mfma_f32_16x16x32_bf16 v[30:33], v[152:155], v[220:223], v[30:33]
	v_mfma_f32_16x16x32_bf16 v[30:33], v[148:151], v[216:219], v[30:33]
	v_mfma_f32_16x16x32_bf16 v[14:17], v[148:151], v[224:227], v[14:17]
	v_mfma_f32_16x16x32_bf16 v[14:17], v[152:155], v[228:231], v[14:17]
	v_mfma_f32_16x16x32_bf16 v[18:21], v[144:147], v[228:231], v[18:21]
	v_mfma_f32_16x16x32_bf16 v[18:21], v[140:143], v[224:227], v[18:21]
	s_setprio 0
	s_setprio 1
	v_mfma_f32_16x16x32_bf16 v[58:61], v[156:159], v[200:203], v[58:61]
	v_mfma_f32_16x16x32_bf16 v[58:61], v[160:163], v[204:207], v[58:61]
	v_mfma_f32_16x16x32_bf16 v[54:57], v[196:199], v[204:207], v[54:57]
	v_mfma_f32_16x16x32_bf16 v[54:57], v[186:189], v[200:203], v[54:57]
	v_mfma_f32_16x16x32_bf16 v[38:41], v[186:189], v[208:211], v[38:41]
	v_mfma_f32_16x16x32_bf16 v[38:41], v[196:199], v[212:215], v[38:41]
	v_mfma_f32_16x16x32_bf16 v[42:45], v[160:163], v[212:215], v[42:45]
	v_mfma_f32_16x16x32_bf16 v[42:45], v[156:159], v[208:211], v[42:45]
	v_mfma_f32_16x16x32_bf16 v[26:29], v[156:159], v[216:219], v[26:29]
	v_mfma_f32_16x16x32_bf16 v[26:29], v[160:163], v[220:223], v[26:29]
	v_mfma_f32_16x16x32_bf16 v[22:25], v[196:199], v[220:223], v[22:25]
	v_mfma_f32_16x16x32_bf16 v[22:25], v[186:189], v[216:219], v[22:25]
	v_mfma_f32_16x16x32_bf16 v[4:7], v[186:189], v[224:227], v[6:9]
	v_mfma_f32_16x16x32_bf16 v[4:7], v[196:199], v[228:231], v[4:7]
	v_mfma_f32_16x16x32_bf16 v[10:13], v[160:163], v[228:231], v[10:13]
	v_mfma_f32_16x16x32_bf16 v[10:13], v[156:159], v[224:227], v[10:13]
	s_setprio 0
	s_barrier
	s_add_i32 s67, 0, 0x18000
	v_add_u32_e32 v3, s67, v167
	s_add_i32 s68, 0, 0x1c000
	ds_read_b128 v[140:143], v3
	ds_read_b128 v[144:147], v3 offset:1024
	ds_read_b128 v[148:151], v3 offset:2048
	ds_read_b128 v[152:155], v3 offset:3072
	v_add_u32_e32 v3, s68, v167
	ds_read_b128 v[156:159], v3
	ds_read_b128 v[160:163], v3 offset:1024
	ds_read_b128 v[186:189], v3 offset:2048
	ds_read_b128 v[196:199], v3 offset:3072
	s_add_u32 s34, s34, 0x600000
	s_addc_u32 s35, s35, 0
	s_mov_b32 m0, s38
	ds_read_b128 v[200:203], v194 offset:32768
	ds_read_b128 v[204:207], v194 offset:33792
	ds_read_b128 v[208:211], v194 offset:34816
	ds_read_b128 v[212:215], v194 offset:35840
	ds_read_b128 v[216:219], v194 offset:36864
	ds_read_b128 v[220:223], v194 offset:37888
	ds_read_b128 v[224:227], v194 offset:38912
	ds_read_b128 v[228:231], v194 offset:39936
	global_load_lds_dwordx4 v168, s[34:35]
	s_mov_b32 m0, s39
	s_nop 0
	global_load_lds_dwordx4 v172, s[34:35]
	s_waitcnt vmcnt(8)
	s_waitcnt lgkmcnt(0)
	s_barrier
	s_setprio 1
	s_waitcnt lgkmcnt(0)
	v_mfma_f32_16x16x32_bf16 v[130:133], v[140:143], v[200:203], v[130:133]
	v_mfma_f32_16x16x32_bf16 v[130:133], v[144:147], v[204:207], v[130:133]
	v_mfma_f32_16x16x32_bf16 v[126:129], v[152:155], v[204:207], v[126:129]
	v_mfma_f32_16x16x32_bf16 v[126:129], v[148:151], v[200:203], v[126:129]
	v_mfma_f32_16x16x32_bf16 v[110:113], v[148:151], v[208:211], v[110:113]
	v_mfma_f32_16x16x32_bf16 v[110:113], v[152:155], v[212:215], v[110:113]
	v_mfma_f32_16x16x32_bf16 v[114:117], v[144:147], v[212:215], v[114:117]
	v_mfma_f32_16x16x32_bf16 v[114:117], v[140:143], v[208:211], v[114:117]
	v_mfma_f32_16x16x32_bf16 v[98:101], v[140:143], v[216:219], v[98:101]
	v_mfma_f32_16x16x32_bf16 v[98:101], v[144:147], v[220:223], v[98:101]
	v_mfma_f32_16x16x32_bf16 v[94:97], v[152:155], v[220:223], v[94:97]
	v_mfma_f32_16x16x32_bf16 v[94:97], v[148:151], v[216:219], v[94:97]
	v_mfma_f32_16x16x32_bf16 v[78:81], v[148:151], v[224:227], v[78:81]
	v_mfma_f32_16x16x32_bf16 v[78:81], v[152:155], v[228:231], v[78:81]
	v_mfma_f32_16x16x32_bf16 v[82:85], v[144:147], v[228:231], v[82:85]
	v_mfma_f32_16x16x32_bf16 v[82:85], v[140:143], v[224:227], v[82:85]
	s_setprio 0
	s_setprio 1
	v_mfma_f32_16x16x32_bf16 v[122:125], v[156:159], v[200:203], v[122:125]
	v_mfma_f32_16x16x32_bf16 v[122:125], v[160:163], v[204:207], v[122:125]
	v_mfma_f32_16x16x32_bf16 v[118:121], v[196:199], v[204:207], v[118:121]
	v_mfma_f32_16x16x32_bf16 v[118:121], v[186:189], v[200:203], v[118:121]
	v_mfma_f32_16x16x32_bf16 v[102:105], v[186:189], v[208:211], v[102:105]
	v_mfma_f32_16x16x32_bf16 v[102:105], v[196:199], v[212:215], v[102:105]
	v_mfma_f32_16x16x32_bf16 v[106:109], v[160:163], v[212:215], v[106:109]
	v_mfma_f32_16x16x32_bf16 v[106:109], v[156:159], v[208:211], v[106:109]
	v_mfma_f32_16x16x32_bf16 v[90:93], v[156:159], v[216:219], v[90:93]
	v_mfma_f32_16x16x32_bf16 v[90:93], v[160:163], v[220:223], v[90:93]
	v_mfma_f32_16x16x32_bf16 v[86:89], v[196:199], v[220:223], v[86:89]
	v_mfma_f32_16x16x32_bf16 v[86:89], v[186:189], v[216:219], v[86:89]
	v_mfma_f32_16x16x32_bf16 v[70:73], v[186:189], v[224:227], v[70:73]
	v_mfma_f32_16x16x32_bf16 v[70:73], v[196:199], v[228:231], v[70:73]
	v_mfma_f32_16x16x32_bf16 v[74:77], v[160:163], v[228:231], v[74:77]
	v_mfma_f32_16x16x32_bf16 v[74:77], v[156:159], v[224:227], v[74:77]
	s_setprio 0
	s_barrier
; #define PG8_STAGE(bufoff, gbase, voff) do { _Pragma("unroll") for (int _i = 0; _i < 2; ++_i) \
;         __builtin_amdgcn_global_load_lds((const unsigned*)((const char*)(gbase) + (voff)[_i]), (PG8_LAS unsigned*)(lds + (bufoff) + ldsw + _i * 8192), 16, 0, 0); } while (0)
; #define PG8_LDA(dst, b, h) do { _Pragma("unroll") for (int m = 0; m < 4; ++m) _Pragma("unroll") for (int k = 0; k < 2; ++k) dst[m][k] = *(const PG8_LAS bf16x8*)(lds + PG8_SA(b, h) + aoff + m * 2048 + k * 1024); } while (0)
; #define PG8_MMA(ai, bj, At, Bt) do { __builtin_amdgcn_s_setprio(1); _Pragma("unroll") for (int m = 0; m < 4; ++m) _Pragma("unroll") for (int n = 0; n < 2; ++n) _Pragma("unroll") for (int k = 0; k < 2; ++k) \
;         acc[ai][bj][m][n] = __builtin_amdgcn_mfma_f32_16x16x32_bf16(Bt[n][k], At[m][k], acc[ai][bj][m][n], 0, 0, 0); __builtin_amdgcn_s_setprio(0); } while (0)
; #define PG8_WAIT_V(n) asm volatile("s_waitcnt vmcnt(" #n ")" ::: "memory")
; #define PG8_WAIT_L(n) asm volatile("s_waitcnt lgkmcnt(" #n ")" ::: "memory")
; #define PG8_BAR __builtin_amdgcn_s_barrier()
; #define PG8_SCHED __builtin_amdgcn_sched_barrier(0)
; template <class Epi, class Sched, bool ALIGN_EPI = false, bool SP2 = false>
; __device__ __forceinline__ void gemm_phase(PG8_LAS unsigned char* lds, const Gemm g, const Sched& S, const Epi& E) {
;     ...
;             PG8_LDA(At, 1, 1); PG8_STAGE(PG8_SB(1, 0), b3, voffB); PG8_STAGE(PG8_SB(1, 1), b3 + hstepB, voffB); PG8_STAGE(PG8_SA(1, 0), a3, voffA);
;             PG8_WAIT_V(8); PG8_WAIT_L(0); PG8_BAR; PG8_MMA(1, 0, At, B0); PG8_MMA(1, 1, At, B1); PG8_BAR; PG8_SCHED;
	s_add_i32 s34, s67, s36
	s_mov_b32 m0, s34
	ds_read_b128 v[200:203], v194 offset:49152
	ds_read_b128 v[204:207], v194 offset:50176
	ds_read_b128 v[208:211], v194 offset:51200
	ds_read_b128 v[212:215], v194 offset:52224
	ds_read_b128 v[216:219], v194 offset:53248
	ds_read_b128 v[220:223], v194 offset:54272
	ds_read_b128 v[224:227], v194 offset:55296
	ds_read_b128 v[228:231], v194 offset:56320
	global_load_lds_dwordx4 v170, s[98:99]
	s_add_i32 m0, s34, 0x2000
	s_add_u32 s30, s30, 0x200080
	s_addc_u32 s31, s31, 0
	s_add_i32 s34, s68, s36
	global_load_lds_dwordx4 v174, s[98:99]
	s_mov_b32 m0, s34
	s_nop 0
	global_load_lds_dwordx4 v170, s[30:31]
	s_add_i32 m0, s34, 0x2000
	s_nop 0
	global_load_lds_dwordx4 v174, s[30:31]
	s_mov_b32 m0, s41
	s_nop 0
	global_load_lds_dwordx4 v168, s[100:101]
	s_mov_b32 m0, s50
	s_nop 0
	global_load_lds_dwordx4 v172, s[100:101]
	s_waitcnt vmcnt(8)
	s_waitcnt lgkmcnt(0)
	s_barrier
	s_setprio 1
	s_waitcnt lgkmcnt(0)
	v_mfma_f32_16x16x32_bf16 v[66:69], v[140:143], v[200:203], v[66:69]
	v_mfma_f32_16x16x32_bf16 v[66:69], v[144:147], v[204:207], v[66:69]
	v_mfma_f32_16x16x32_bf16 v[62:65], v[152:155], v[204:207], v[62:65]
	v_mfma_f32_16x16x32_bf16 v[62:65], v[148:151], v[200:203], v[62:65]
	v_mfma_f32_16x16x32_bf16 v[46:49], v[148:151], v[208:211], v[46:49]
	v_mfma_f32_16x16x32_bf16 v[46:49], v[152:155], v[212:215], v[46:49]
	v_mfma_f32_16x16x32_bf16 v[50:53], v[144:147], v[212:215], v[50:53]
	v_mfma_f32_16x16x32_bf16 v[50:53], v[140:143], v[208:211], v[50:53]
	v_mfma_f32_16x16x32_bf16 v[34:37], v[140:143], v[216:219], v[34:37]
	v_mfma_f32_16x16x32_bf16 v[34:37], v[144:147], v[220:223], v[34:37]
	v_mfma_f32_16x16x32_bf16 v[30:33], v[152:155], v[220:223], v[30:33]
	v_mfma_f32_16x16x32_bf16 v[30:33], v[148:151], v[216:219], v[30:33]
	v_mfma_f32_16x16x32_bf16 v[14:17], v[148:151], v[224:227], v[14:17]
	v_mfma_f32_16x16x32_bf16 v[14:17], v[152:155], v[228:231], v[14:17]
	v_mfma_f32_16x16x32_bf16 v[18:21], v[144:147], v[228:231], v[18:21]
	v_mfma_f32_16x16x32_bf16 v[18:21], v[140:143], v[224:227], v[18:21]
	s_setprio 0
	s_setprio 1
	v_mfma_f32_16x16x32_bf16 v[58:61], v[156:159], v[200:203], v[58:61]
	v_mfma_f32_16x16x32_bf16 v[58:61], v[160:163], v[204:207], v[58:61]
	v_mfma_f32_16x16x32_bf16 v[54:57], v[196:199], v[204:207], v[54:57]
	v_mfma_f32_16x16x32_bf16 v[54:57], v[186:189], v[200:203], v[54:57]
	v_mfma_f32_16x16x32_bf16 v[38:41], v[186:189], v[208:211], v[38:41]
	v_mfma_f32_16x16x32_bf16 v[38:41], v[196:199], v[212:215], v[38:41]
	v_mfma_f32_16x16x32_bf16 v[42:45], v[160:163], v[212:215], v[42:45]
	v_mfma_f32_16x16x32_bf16 v[42:45], v[156:159], v[208:211], v[42:45]
	v_mfma_f32_16x16x32_bf16 v[26:29], v[156:159], v[216:219], v[26:29]
	v_mfma_f32_16x16x32_bf16 v[26:29], v[160:163], v[220:223], v[26:29]
	v_mfma_f32_16x16x32_bf16 v[22:25], v[196:199], v[220:223], v[22:25]
	v_mfma_f32_16x16x32_bf16 v[22:25], v[186:189], v[216:219], v[22:25]
	v_mfma_f32_16x16x32_bf16 v[8:11], v[156:159], v[224:227], v[10:13]
	v_mfma_f32_16x16x32_bf16 v[10:13], v[160:163], v[228:231], v[8:11]
	v_mfma_f32_16x16x32_bf16 v[4:7], v[186:189], v[224:227], v[4:7]
	v_mfma_f32_16x16x32_bf16 v[6:9], v[196:199], v[228:231], v[4:7]
	s_setprio 0
	s_barrier
	s_add_u32 s4, s4, 0x100
	s_addc_u32 s5, 0, s5
	s_cmpk_gt_u32 s65, 0x7d
	s_cbranch_scc0 .LBB0_434
	s_and_b64 vcc, exec, s[16:17]
	s_cbranch_vccz .LBB0_439
	s_barrier

; #define PG8_STAGE(bufoff, gbase, voff) do { _Pragma("unroll") for (int _i = 0; _i < 2; ++_i) \
;         __builtin_amdgcn_global_load_lds((const unsigned*)((const char*)(gbase) + (voff)[_i]), (PG8_LAS unsigned*)(lds + (bufoff) + ldsw + _i * 8192), 16, 0, 0); } while (0)
; #define PG8_LDA(dst, b, h) do { _Pragma("unroll") for (int m = 0; m < 4; ++m) _Pragma("unroll") for (int k = 0; k < 2; ++k) dst[m][k] = *(const PG8_LAS bf16x8*)(lds + PG8_SA(b, h) + aoff + m * 2048 + k * 1024); } while (0)
; #define PG8_LDB(dst, b, h) do { _Pragma("unroll") for (int n = 0; n < 2; ++n) _Pragma("unroll") for (int k = 0; k < 2; ++k) dst[n][k] = *(const PG8_LAS bf16x8*)(lds + PG8_SB(b, h) + boff + n * 2048 + k * 1024); } while (0)
; #define PG8_MMA(ai, bj, At, Bt) do { __builtin_amdgcn_s_setprio(1); _Pragma("unroll") for (int m = 0; m < 4; ++m) _Pragma("unroll") for (int n = 0; n < 2; ++n) _Pragma("unroll") for (int k = 0; k < 2; ++k) \
;         acc[ai][bj][m][n] = __builtin_amdgcn_mfma_f32_16x16x32_bf16(Bt[n][k], At[m][k], acc[ai][bj][m][n], 0, 0, 0); __builtin_amdgcn_s_setprio(0); } while (0)
; #define PG8_WAIT_V(n) asm volatile("s_waitcnt vmcnt(" #n ")" ::: "memory")
; #define PG8_WAIT_L(n) asm volatile("s_waitcnt lgkmcnt(" #n ")" ::: "memory")
; #define PG8_BAR __builtin_amdgcn_s_barrier()
; #define PG8_SCHED __builtin_amdgcn_sched_barrier(0)
; template <class Epi, class Sched, bool ALIGN_EPI = false, bool SP2 = false>
; __device__ __forceinline__ void gemm_phase(PG8_LAS unsigned char* lds, const Gemm g, const Sched& S, const Epi& E) {
;     ...
;             PG8_LDB(B0, 0, 0); PG8_LDB(B1, 0, 1); PG8_SCHED; PG8_LDA(At, 0, 0); PG8_STAGE(PG8_SA(1, 1), a1 + hstepA, voffA);
;             PG8_WAIT_V(8); PG8_WAIT_L(0); PG8_BAR; PG8_MMA(0, 0, At, B0); PG8_MMA(0, 1, At, B1); PG8_BAR; PG8_SCHED;
;             PG8_LDA(At, 0, 1); PG8_STAGE(PG8_SB(0, 0), b2, voffB); PG8_STAGE(PG8_SB(0, 1), b2 + hstepB, voffB); PG8_STAGE(PG8_SA(0, 0), a2, voffA);
.LBB0_525:
	ds_read_b128 v[146:149], v160
	ds_read_b128 v[168:171], v160 offset:1024
	ds_read_b128 v[172:175], v160 offset:2048
	ds_read_b128 v[176:179], v160 offset:3072
	ds_read_b128 v[180:183], v161
	ds_read_b128 v[184:187], v161 offset:1024
	ds_read_b128 v[188:191], v161 offset:2048
	ds_read_b128 v[192:195], v161 offset:3072
	s_add_u32 s24, s22, 0xfff00080
	s_addc_u32 s25, s23, -1
	s_cmp_eq_u32 s60, 60
	s_cselect_b32 s27, s15, s25
	s_cselect_b32 s26, s50, s24
	s_cselect_b32 s25, s13, s53
	s_cselect_b32 s24, s51, s52
	s_add_u32 s98, s24, 0x80
	s_addc_u32 s99, s25, 0
	s_add_u32 s100, s26, 0x80
	s_addc_u32 s101, s27, 0
	s_add_i32 m0, s21, 0xc000
	ds_read_b128 v[196:199], v162
	ds_read_b128 v[200:203], v162 offset:1024
	ds_read_b128 v[204:207], v162 offset:2048
	ds_read_b128 v[208:211], v162 offset:3072
	ds_read_b128 v[212:215], v162 offset:4096
	ds_read_b128 v[216:219], v162 offset:5120
	ds_read_b128 v[220:223], v162 offset:6144
	ds_read_b128 v[224:227], v162 offset:7168
	global_load_lds_dwordx4 v138, s[22:23]
	s_add_i32 m0, s21, 0xe000
	s_nop 0
	global_load_lds_dwordx4 v140, s[22:23]
	s_waitcnt vmcnt(8)
	s_waitcnt lgkmcnt(0)
	s_barrier
	s_setprio 1
	s_waitcnt lgkmcnt(0)
	v_mfma_f32_16x16x32_bf16 v[126:129], v[146:149], v[196:199], v[126:129]
	v_mfma_f32_16x16x32_bf16 v[126:129], v[168:171], v[200:203], v[126:129]
	v_mfma_f32_16x16x32_bf16 v[122:125], v[176:179], v[200:203], v[122:125]
	v_mfma_f32_16x16x32_bf16 v[122:125], v[172:175], v[196:199], v[122:125]
	v_mfma_f32_16x16x32_bf16 v[114:117], v[172:175], v[204:207], v[114:117]
	v_mfma_f32_16x16x32_bf16 v[114:117], v[176:179], v[208:211], v[114:117]
	v_mfma_f32_16x16x32_bf16 v[118:121], v[168:171], v[208:211], v[118:121]
	v_mfma_f32_16x16x32_bf16 v[118:121], v[146:149], v[204:207], v[118:121]
	v_mfma_f32_16x16x32_bf16 v[110:113], v[146:149], v[212:215], v[110:113]
	v_mfma_f32_16x16x32_bf16 v[110:113], v[168:171], v[216:219], v[110:113]
	v_mfma_f32_16x16x32_bf16 v[98:101], v[176:179], v[216:219], v[98:101]
	v_mfma_f32_16x16x32_bf16 v[98:101], v[172:175], v[212:215], v[98:101]
	v_mfma_f32_16x16x32_bf16 v[78:81], v[172:175], v[220:223], v[78:81]
	v_mfma_f32_16x16x32_bf16 v[78:81], v[176:179], v[224:227], v[78:81]
	v_mfma_f32_16x16x32_bf16 v[82:85], v[168:171], v[224:227], v[82:85]
	v_mfma_f32_16x16x32_bf16 v[82:85], v[146:149], v[220:223], v[82:85]
	s_setprio 0
	s_setprio 1
	v_mfma_f32_16x16x32_bf16 v[106:109], v[180:183], v[196:199], v[106:109]
	v_mfma_f32_16x16x32_bf16 v[106:109], v[184:187], v[200:203], v[106:109]
	v_mfma_f32_16x16x32_bf16 v[102:105], v[192:195], v[200:203], v[102:105]
	v_mfma_f32_16x16x32_bf16 v[102:105], v[188:191], v[196:199], v[102:105]
	v_mfma_f32_16x16x32_bf16 v[90:93], v[188:191], v[204:207], v[90:93]
	v_mfma_f32_16x16x32_bf16 v[90:93], v[192:195], v[208:211], v[90:93]
	v_mfma_f32_16x16x32_bf16 v[94:97], v[184:187], v[208:211], v[94:97]
	v_mfma_f32_16x16x32_bf16 v[94:97], v[180:183], v[204:207], v[94:97]
	v_mfma_f32_16x16x32_bf16 v[86:89], v[180:183], v[212:215], v[86:89]
	v_mfma_f32_16x16x32_bf16 v[86:89], v[184:187], v[216:219], v[86:89]
	v_mfma_f32_16x16x32_bf16 v[74:77], v[192:195], v[216:219], v[74:77]
	v_mfma_f32_16x16x32_bf16 v[74:77], v[188:191], v[212:215], v[74:77]
	v_mfma_f32_16x16x32_bf16 v[66:69], v[188:191], v[220:223], v[66:69]
	v_mfma_f32_16x16x32_bf16 v[66:69], v[192:195], v[224:227], v[66:69]
	v_mfma_f32_16x16x32_bf16 v[70:73], v[184:187], v[224:227], v[70:73]
	v_mfma_f32_16x16x32_bf16 v[70:73], v[180:183], v[220:223], v[70:73]
	s_setprio 0
	s_barrier
	s_add_i32 s61, s38, s3
	s_mov_b32 m0, s61
	ds_read_b128 v[196:199], v162 offset:16384
	ds_read_b128 v[200:203], v162 offset:17408
	ds_read_b128 v[204:207], v162 offset:18432
	ds_read_b128 v[208:211], v162 offset:19456
	ds_read_b128 v[212:215], v162 offset:20480
	ds_read_b128 v[216:219], v162 offset:21504
	ds_read_b128 v[220:223], v162 offset:22528
	ds_read_b128 v[224:227], v162 offset:23552
	global_load_lds_dwordx4 v136, s[24:25]
	s_add_i32 m0, s61, 0x2000
	s_add_u32 s62, s24, 0x100000
	s_addc_u32 s63, s25, 0
	s_add_i32 s61, s39, s3
	global_load_lds_dwordx4 v134, s[24:25]
	s_mov_b32 m0, s61
	s_nop 0
	global_load_lds_dwordx4 v136, s[62:63]
	s_add_i32 m0, s61, 0x2000
	s_nop 0
	global_load_lds_dwordx4 v134, s[62:63]
	s_mov_b32 m0, s21
	s_nop 0
	global_load_lds_dwordx4 v130, s[26:27]
	s_mov_b32 m0, s30
	s_nop 0
	global_load_lds_dwordx4 v132, s[26:27]
	s_waitcnt vmcnt(8)
	s_waitcnt lgkmcnt(0)
	s_barrier
	s_setprio 1
	s_waitcnt lgkmcnt(0)
	v_mfma_f32_16x16x32_bf16 v[62:65], v[146:149], v[196:199], v[62:65]
	v_mfma_f32_16x16x32_bf16 v[62:65], v[168:171], v[200:203], v[62:65]
	v_mfma_f32_16x16x32_bf16 v[58:61], v[176:179], v[200:203], v[58:61]
	v_mfma_f32_16x16x32_bf16 v[58:61], v[172:175], v[196:199], v[58:61]
	v_mfma_f32_16x16x32_bf16 v[46:49], v[172:175], v[204:207], v[46:49]
	v_mfma_f32_16x16x32_bf16 v[46:49], v[176:179], v[208:211], v[46:49]
	v_mfma_f32_16x16x32_bf16 v[54:57], v[168:171], v[208:211], v[54:57]
	v_mfma_f32_16x16x32_bf16 v[54:57], v[146:149], v[204:207], v[54:57]
	v_mfma_f32_16x16x32_bf16 v[38:41], v[146:149], v[212:215], v[38:41]
	v_mfma_f32_16x16x32_bf16 v[38:41], v[168:171], v[216:219], v[38:41]
	v_mfma_f32_16x16x32_bf16 v[30:33], v[176:179], v[216:219], v[30:33]
	v_mfma_f32_16x16x32_bf16 v[30:33], v[172:175], v[212:215], v[30:33]
	v_mfma_f32_16x16x32_bf16 v[14:17], v[172:175], v[220:223], v[14:17]
	v_mfma_f32_16x16x32_bf16 v[14:17], v[176:179], v[224:227], v[14:17]
	v_mfma_f32_16x16x32_bf16 v[22:25], v[168:171], v[224:227], v[22:25]
	v_mfma_f32_16x16x32_bf16 v[22:25], v[146:149], v[220:223], v[22:25]
	s_setprio 0
	s_setprio 1
	v_mfma_f32_16x16x32_bf16 v[50:53], v[180:183], v[196:199], v[50:53]
	v_mfma_f32_16x16x32_bf16 v[50:53], v[184:187], v[200:203], v[50:53]
	v_mfma_f32_16x16x32_bf16 v[42:45], v[192:195], v[200:203], v[42:45]
	v_mfma_f32_16x16x32_bf16 v[42:45], v[188:191], v[196:199], v[42:45]
	v_mfma_f32_16x16x32_bf16 v[26:29], v[188:191], v[204:207], v[26:29]
	v_mfma_f32_16x16x32_bf16 v[26:29], v[192:195], v[208:211], v[26:29]
	v_mfma_f32_16x16x32_bf16 v[34:37], v[184:187], v[208:211], v[34:37]
	v_mfma_f32_16x16x32_bf16 v[34:37], v[180:183], v[204:207], v[34:37]
	v_mfma_f32_16x16x32_bf16 v[18:21], v[180:183], v[212:215], v[18:21]
	v_mfma_f32_16x16x32_bf16 v[18:21], v[184:187], v[216:219], v[18:21]
	v_mfma_f32_16x16x32_bf16 v[10:13], v[192:195], v[216:219], v[10:13]
	v_mfma_f32_16x16x32_bf16 v[10:13], v[188:191], v[212:215], v[10:13]
	v_mfma_f32_16x16x32_bf16 v[2:5], v[188:191], v[220:223], v[2:5]
	v_mfma_f32_16x16x32_bf16 v[2:5], v[192:195], v[224:227], v[2:5]
	v_mfma_f32_16x16x32_bf16 v[6:9], v[184:187], v[224:227], v[6:9]
	v_mfma_f32_16x16x32_bf16 v[6:9], v[180:183], v[220:223], v[6:9]
	s_setprio 0
	s_barrier
; #define PG8_STAGE(bufoff, gbase, voff) do { _Pragma("unroll") for (int _i = 0; _i < 2; ++_i) \
;         __builtin_amdgcn_global_load_lds((const unsigned*)((const char*)(gbase) + (voff)[_i]), (PG8_LAS unsigned*)(lds + (bufoff) + ldsw + _i * 8192), 16, 0, 0); } while (0)
; #define PG8_LDA(dst, b, h) do { _Pragma("unroll") for (int m = 0; m < 4; ++m) _Pragma("unroll") for (int k = 0; k < 2; ++k) dst[m][k] = *(const PG8_LAS bf16x8*)(lds + PG8_SA(b, h) + aoff + m * 2048 + k * 1024); } while (0)
; #define PG8_LDB(dst, b, h) do { _Pragma("unroll") for (int n = 0; n < 2; ++n) _Pragma("unroll") for (int k = 0; k < 2; ++k) dst[n][k] = *(const PG8_LAS bf16x8*)(lds + PG8_SB(b, h) + boff + n * 2048 + k * 1024); } while (0)
; #define PG8_MMA(ai, bj, At, Bt) do { __builtin_amdgcn_s_setprio(1); _Pragma("unroll") for (int m = 0; m < 4; ++m) _Pragma("unroll") for (int n = 0; n < 2; ++n) _Pragma("unroll") for (int k = 0; k < 2; ++k) \
;         acc[ai][bj][m][n] = __builtin_amdgcn_mfma_f32_16x16x32_bf16(Bt[n][k], At[m][k], acc[ai][bj][m][n], 0, 0, 0); __builtin_amdgcn_s_setprio(0); } while (0)
; #define PG8_WAIT_V(n) asm volatile("s_waitcnt vmcnt(" #n ")" ::: "memory")
; #define PG8_WAIT_L(n) asm volatile("s_waitcnt lgkmcnt(" #n ")" ::: "memory")
; #define PG8_BAR __builtin_amdgcn_s_barrier()
; #define PG8_SCHED __builtin_amdgcn_sched_barrier(0)
; template <class Epi, class Sched, bool ALIGN_EPI = false, bool SP2 = false>
; __device__ __forceinline__ void gemm_phase(PG8_LAS unsigned char* lds, const Gemm g, const Sched& S, const Epi& E) {
;     ...
;             PG8_LDB(B0, 1, 0); PG8_LDB(B1, 1, 1); PG8_SCHED; PG8_LDA(At, 1, 0); PG8_STAGE(PG8_SA(0, 1), a2 + hstepA, voffA);
;             PG8_WAIT_V(8); PG8_WAIT_L(0); PG8_BAR; PG8_MMA(0, 0, At, B0); PG8_MMA(0, 1, At, B1); PG8_BAR; PG8_SCHED;
;             PG8_LDA(At, 1, 1); PG8_STAGE(PG8_SB(1, 0), b3, voffB); PG8_STAGE(PG8_SB(1, 1), b3 + hstepB, voffB); PG8_STAGE(PG8_SA(1, 0), a3, voffA);
;             PG8_WAIT_V(8); PG8_WAIT_L(0); PG8_BAR; PG8_MMA(1, 0, At, B0); PG8_MMA(1, 1, At, B1); PG8_BAR; PG8_SCHED;
	s_add_i32 s61, 0, 0x18000
	v_add_u32_e32 v150, s61, v158
	s_add_i32 s62, 0, 0x1c000
	ds_read_b128 v[146:149], v150
	ds_read_b128 v[168:171], v150 offset:1024
	ds_read_b128 v[172:175], v150 offset:2048
	ds_read_b128 v[176:179], v150 offset:3072
	v_add_u32_e32 v150, s62, v158
	ds_read_b128 v[180:183], v150
	ds_read_b128 v[184:187], v150 offset:1024
	ds_read_b128 v[188:191], v150 offset:2048
	ds_read_b128 v[192:195], v150 offset:3072
	s_add_u32 s26, s26, 0x100000
	s_addc_u32 s27, s27, 0
	s_mov_b32 m0, s31
	ds_read_b128 v[196:199], v162 offset:32768
	ds_read_b128 v[200:203], v162 offset:33792
	ds_read_b128 v[204:207], v162 offset:34816
	ds_read_b128 v[208:211], v162 offset:35840
	ds_read_b128 v[212:215], v162 offset:36864
	ds_read_b128 v[216:219], v162 offset:37888
	ds_read_b128 v[220:223], v162 offset:38912
	ds_read_b128 v[224:227], v162 offset:39936
	global_load_lds_dwordx4 v130, s[26:27]
	s_mov_b32 m0, s33
	s_nop 0
	global_load_lds_dwordx4 v132, s[26:27]
	s_waitcnt vmcnt(8)
	s_waitcnt lgkmcnt(0)
	s_barrier
	s_setprio 1
	s_waitcnt lgkmcnt(0)
	v_mfma_f32_16x16x32_bf16 v[126:129], v[146:149], v[196:199], v[126:129]
	v_mfma_f32_16x16x32_bf16 v[126:129], v[168:171], v[200:203], v[126:129]
	v_mfma_f32_16x16x32_bf16 v[122:125], v[176:179], v[200:203], v[122:125]
	v_mfma_f32_16x16x32_bf16 v[122:125], v[172:175], v[196:199], v[122:125]
	v_mfma_f32_16x16x32_bf16 v[114:117], v[172:175], v[204:207], v[114:117]
	v_mfma_f32_16x16x32_bf16 v[114:117], v[176:179], v[208:211], v[114:117]
	v_mfma_f32_16x16x32_bf16 v[118:121], v[168:171], v[208:211], v[118:121]
	v_mfma_f32_16x16x32_bf16 v[118:121], v[146:149], v[204:207], v[118:121]
	v_mfma_f32_16x16x32_bf16 v[110:113], v[146:149], v[212:215], v[110:113]
	v_mfma_f32_16x16x32_bf16 v[110:113], v[168:171], v[216:219], v[110:113]
	v_mfma_f32_16x16x32_bf16 v[98:101], v[176:179], v[216:219], v[98:101]
	v_mfma_f32_16x16x32_bf16 v[98:101], v[172:175], v[212:215], v[98:101]
	v_mfma_f32_16x16x32_bf16 v[78:81], v[172:175], v[220:223], v[78:81]
	v_mfma_f32_16x16x32_bf16 v[78:81], v[176:179], v[224:227], v[78:81]
	v_mfma_f32_16x16x32_bf16 v[82:85], v[168:171], v[224:227], v[82:85]
	v_mfma_f32_16x16x32_bf16 v[82:85], v[146:149], v[220:223], v[82:85]
	s_setprio 0
	s_setprio 1
	v_mfma_f32_16x16x32_bf16 v[106:109], v[180:183], v[196:199], v[106:109]
	v_mfma_f32_16x16x32_bf16 v[106:109], v[184:187], v[200:203], v[106:109]
	v_mfma_f32_16x16x32_bf16 v[102:105], v[192:195], v[200:203], v[102:105]
	v_mfma_f32_16x16x32_bf16 v[102:105], v[188:191], v[196:199], v[102:105]
	v_mfma_f32_16x16x32_bf16 v[90:93], v[188:191], v[204:207], v[90:93]
	v_mfma_f32_16x16x32_bf16 v[90:93], v[192:195], v[208:211], v[90:93]
	v_mfma_f32_16x16x32_bf16 v[94:97], v[184:187], v[208:211], v[94:97]
	v_mfma_f32_16x16x32_bf16 v[94:97], v[180:183], v[204:207], v[94:97]
	v_mfma_f32_16x16x32_bf16 v[86:89], v[180:183], v[212:215], v[86:89]
	v_mfma_f32_16x16x32_bf16 v[86:89], v[184:187], v[216:219], v[86:89]
	v_mfma_f32_16x16x32_bf16 v[74:77], v[192:195], v[216:219], v[74:77]
	v_mfma_f32_16x16x32_bf16 v[74:77], v[188:191], v[212:215], v[74:77]
	v_mfma_f32_16x16x32_bf16 v[66:69], v[188:191], v[220:223], v[66:69]
	v_mfma_f32_16x16x32_bf16 v[66:69], v[192:195], v[224:227], v[66:69]
	v_mfma_f32_16x16x32_bf16 v[70:73], v[184:187], v[224:227], v[70:73]
	v_mfma_f32_16x16x32_bf16 v[70:73], v[180:183], v[220:223], v[70:73]
	s_setprio 0
	s_barrier
	s_add_i32 s26, s61, s3
	s_mov_b32 m0, s26
	ds_read_b128 v[196:199], v162 offset:49152
	ds_read_b128 v[200:203], v162 offset:50176
	ds_read_b128 v[204:207], v162 offset:51200
	ds_read_b128 v[208:211], v162 offset:52224
	ds_read_b128 v[212:215], v162 offset:53248
	ds_read_b128 v[216:219], v162 offset:54272
	ds_read_b128 v[220:223], v162 offset:55296
	ds_read_b128 v[224:227], v162 offset:56320
	global_load_lds_dwordx4 v136, s[98:99]
	s_add_i32 m0, s26, 0x2000
	s_add_u32 s24, s24, 0x100080
	s_addc_u32 s25, s25, 0
	s_add_i32 s26, s62, s3
	global_load_lds_dwordx4 v134, s[98:99]
	s_mov_b32 m0, s26
	s_nop 0
	global_load_lds_dwordx4 v136, s[24:25]
	s_add_i32 m0, s26, 0x2000
	s_nop 0
	global_load_lds_dwordx4 v134, s[24:25]
	s_mov_b32 m0, s35
	s_nop 0
	global_load_lds_dwordx4 v130, s[100:101]
	s_mov_b32 m0, s36
	s_nop 0
	global_load_lds_dwordx4 v132, s[100:101]
	s_waitcnt vmcnt(8)
	s_waitcnt lgkmcnt(0)
	s_barrier
	s_setprio 1
	s_waitcnt lgkmcnt(0)
	v_mfma_f32_16x16x32_bf16 v[62:65], v[146:149], v[196:199], v[62:65]
	v_mfma_f32_16x16x32_bf16 v[62:65], v[168:171], v[200:203], v[62:65]
	v_mfma_f32_16x16x32_bf16 v[58:61], v[176:179], v[200:203], v[58:61]
	v_mfma_f32_16x16x32_bf16 v[58:61], v[172:175], v[196:199], v[58:61]
	v_mfma_f32_16x16x32_bf16 v[46:49], v[172:175], v[204:207], v[46:49]
	v_mfma_f32_16x16x32_bf16 v[46:49], v[176:179], v[208:211], v[46:49]
	v_mfma_f32_16x16x32_bf16 v[54:57], v[168:171], v[208:211], v[54:57]
	v_mfma_f32_16x16x32_bf16 v[54:57], v[146:149], v[204:207], v[54:57]
	v_mfma_f32_16x16x32_bf16 v[38:41], v[146:149], v[212:215], v[38:41]
	v_mfma_f32_16x16x32_bf16 v[38:41], v[168:171], v[216:219], v[38:41]
	v_mfma_f32_16x16x32_bf16 v[30:33], v[176:179], v[216:219], v[30:33]
	v_mfma_f32_16x16x32_bf16 v[30:33], v[172:175], v[212:215], v[30:33]
	v_mfma_f32_16x16x32_bf16 v[14:17], v[172:175], v[220:223], v[14:17]
	v_mfma_f32_16x16x32_bf16 v[14:17], v[176:179], v[224:227], v[14:17]
	v_mfma_f32_16x16x32_bf16 v[22:25], v[168:171], v[224:227], v[22:25]
	v_mfma_f32_16x16x32_bf16 v[22:25], v[146:149], v[220:223], v[22:25]
	s_setprio 0
	s_setprio 1
	v_mfma_f32_16x16x32_bf16 v[50:53], v[180:183], v[196:199], v[50:53]
	v_mfma_f32_16x16x32_bf16 v[50:53], v[184:187], v[200:203], v[50:53]
	v_mfma_f32_16x16x32_bf16 v[42:45], v[192:195], v[200:203], v[42:45]
	v_mfma_f32_16x16x32_bf16 v[42:45], v[188:191], v[196:199], v[42:45]
	v_mfma_f32_16x16x32_bf16 v[26:29], v[188:191], v[204:207], v[26:29]
	v_mfma_f32_16x16x32_bf16 v[26:29], v[192:195], v[208:211], v[26:29]
	v_mfma_f32_16x16x32_bf16 v[34:37], v[184:187], v[208:211], v[34:37]
	v_mfma_f32_16x16x32_bf16 v[34:37], v[180:183], v[204:207], v[34:37]
	v_mfma_f32_16x16x32_bf16 v[18:21], v[180:183], v[212:215], v[18:21]
	v_mfma_f32_16x16x32_bf16 v[18:21], v[184:187], v[216:219], v[18:21]
	v_mfma_f32_16x16x32_bf16 v[10:13], v[192:195], v[216:219], v[10:13]
	v_mfma_f32_16x16x32_bf16 v[10:13], v[188:191], v[212:215], v[10:13]
	v_mfma_f32_16x16x32_bf16 v[2:5], v[188:191], v[220:223], v[2:5]
	v_mfma_f32_16x16x32_bf16 v[2:5], v[192:195], v[224:227], v[2:5]
	v_mfma_f32_16x16x32_bf16 v[6:9], v[184:187], v[224:227], v[6:9]
	v_mfma_f32_16x16x32_bf16 v[6:9], v[180:183], v[220:223], v[6:9]
	s_setprio 0
	s_barrier
	s_add_i32 s60, s60, 2
	s_add_u32 s22, s22, 0x100
	s_addc_u32 s23, s23, 0
	s_add_u32 s52, s52, 0x100
	s_addc_u32 s53, s53, 0
	s_cmp_gt_u32 s60, 61
	s_cbranch_scc0 .LBB0_525
	s_and_b64 vcc, exec, s[10:11]
	s_cbranch_vccz .LBB0_528
	s_barrier

; #define PG8_STAGE(bufoff, gbase, voff) do { _Pragma("unroll") for (int _i = 0; _i < 2; ++_i) \
;         __builtin_amdgcn_global_load_lds((const unsigned*)((const char*)(gbase) + (voff)[_i]), (PG8_LAS unsigned*)(lds + (bufoff) + ldsw + _i * 8192), 16, 0, 0); } while (0)
; #define PG8_LDA(dst, b, h) do { _Pragma("unroll") for (int m = 0; m < 4; ++m) _Pragma("unroll") for (int k = 0; k < 2; ++k) dst[m][k] = *(const PG8_LAS bf16x8*)(lds + PG8_SA(b, h) + aoff + m * 2048 + k * 1024); } while (0)
; #define PG8_LDB(dst, b, h) do { _Pragma("unroll") for (int n = 0; n < 2; ++n) _Pragma("unroll") for (int k = 0; k < 2; ++k) dst[n][k] = *(const PG8_LAS bf16x8*)(lds + PG8_SB(b, h) + boff + n * 2048 + k * 1024); } while (0)
; #define PG8_MMA(ai, bj, At, Bt) do { __builtin_amdgcn_s_setprio(1); _Pragma("unroll") for (int m = 0; m < 4; ++m) _Pragma("unroll") for (int n = 0; n < 2; ++n) _Pragma("unroll") for (int k = 0; k < 2; ++k) \
;         acc[ai][bj][m][n] = __builtin_amdgcn_mfma_f32_16x16x32_bf16(Bt[n][k], At[m][k], acc[ai][bj][m][n], 0, 0, 0); __builtin_amdgcn_s_setprio(0); } while (0)
; #define PG8_WAIT_V(n) asm volatile("s_waitcnt vmcnt(" #n ")" ::: "memory")
; #define PG8_WAIT_L(n) asm volatile("s_waitcnt lgkmcnt(" #n ")" ::: "memory")
; #define PG8_BAR __builtin_amdgcn_s_barrier()
; #define PG8_SCHED __builtin_amdgcn_sched_barrier(0)
; template <class Epi, class Sched, bool ALIGN_EPI = false, bool SP2 = false>
; __device__ __forceinline__ void gemm_phase(PG8_LAS unsigned char* lds, const Gemm g, const Sched& S, const Epi& E) {
;     ...
;             PG8_LDB(B0, 0, 0); PG8_LDB(B1, 0, 1); PG8_SCHED; PG8_LDA(At, 0, 0); PG8_STAGE(PG8_SA(1, 1), a1 + hstepA, voffA);
;             PG8_WAIT_V(8); PG8_WAIT_L(0); PG8_BAR; PG8_MMA(0, 0, At, B0); PG8_MMA(0, 1, At, B1); PG8_BAR; PG8_SCHED;
;             PG8_LDA(At, 0, 1); PG8_STAGE(PG8_SB(0, 0), b2, voffB); PG8_STAGE(PG8_SB(0, 1), b2 + hstepB, voffB); PG8_STAGE(PG8_SA(0, 0), a2, voffA);
.LBB0_882:
	ds_read_b128 v[128:131], v192
	ds_read_b128 v[132:135], v192 offset:1024
	ds_read_b128 v[136:139], v192 offset:2048
	ds_read_b128 v[140:143], v192 offset:3072
	ds_read_b128 v[160:163], v193
	ds_read_b128 v[168:171], v193 offset:1024
	ds_read_b128 v[172:175], v193 offset:2048
	ds_read_b128 v[176:179], v193 offset:3072
	s_add_u32 s36, s6, 0xffb70080
	s_addc_u32 s37, s7, -1
	s_cmpk_eq_i32 s65, 0x7c
	s_cselect_b32 s39, s29, s37
	s_cselect_b32 s38, s28, s36
	s_cselect_b32 s37, s27, s64
	s_cselect_b32 s36, s35, s63
	s_add_u32 s98, s36, 0x80
	s_addc_u32 s99, s37, 0
	s_add_u32 s100, s38, 0x80
	s_addc_u32 s101, s39, 0
	s_add_i32 m0, s41, 0xc000
	ds_read_b128 v[180:183], v194
	ds_read_b128 v[184:187], v194 offset:1024
	ds_read_b128 v[196:199], v194 offset:2048
	ds_read_b128 v[200:203], v194 offset:3072
	ds_read_b128 v[204:207], v194 offset:4096
	ds_read_b128 v[208:211], v194 offset:5120
	ds_read_b128 v[212:215], v194 offset:6144
	ds_read_b128 v[216:219], v194 offset:7168
	global_load_lds_dwordx4 v152, s[6:7]
	s_add_i32 m0, s41, 0xe000
	s_nop 0
	global_load_lds_dwordx4 v154, s[6:7]
	s_waitcnt vmcnt(8)
	s_waitcnt lgkmcnt(0)
	s_barrier
	s_setprio 1
	s_waitcnt lgkmcnt(0)
	v_mfma_f32_16x16x32_bf16 v[124:127], v[128:131], v[180:183], v[124:127]
	v_mfma_f32_16x16x32_bf16 v[124:127], v[132:135], v[184:187], v[124:127]
	v_mfma_f32_16x16x32_bf16 v[120:123], v[140:143], v[184:187], v[120:123]
	v_mfma_f32_16x16x32_bf16 v[120:123], v[136:139], v[180:183], v[120:123]
	v_mfma_f32_16x16x32_bf16 v[104:107], v[136:139], v[196:199], v[104:107]
	v_mfma_f32_16x16x32_bf16 v[104:107], v[140:143], v[200:203], v[104:107]
	v_mfma_f32_16x16x32_bf16 v[108:111], v[132:135], v[200:203], v[108:111]
	v_mfma_f32_16x16x32_bf16 v[108:111], v[128:131], v[196:199], v[108:111]
	v_mfma_f32_16x16x32_bf16 v[92:95], v[128:131], v[204:207], v[92:95]
	v_mfma_f32_16x16x32_bf16 v[92:95], v[132:135], v[208:211], v[92:95]
	v_mfma_f32_16x16x32_bf16 v[88:91], v[140:143], v[208:211], v[88:91]
	v_mfma_f32_16x16x32_bf16 v[88:91], v[136:139], v[204:207], v[88:91]
	v_mfma_f32_16x16x32_bf16 v[72:75], v[136:139], v[212:215], v[72:75]
	v_mfma_f32_16x16x32_bf16 v[72:75], v[140:143], v[216:219], v[72:75]
	v_mfma_f32_16x16x32_bf16 v[76:79], v[132:135], v[216:219], v[76:79]
	v_mfma_f32_16x16x32_bf16 v[76:79], v[128:131], v[212:215], v[76:79]
	s_setprio 0
	s_setprio 1
	v_mfma_f32_16x16x32_bf16 v[116:119], v[160:163], v[180:183], v[116:119]
	v_mfma_f32_16x16x32_bf16 v[116:119], v[168:171], v[184:187], v[116:119]
	v_mfma_f32_16x16x32_bf16 v[112:115], v[176:179], v[184:187], v[112:115]
	v_mfma_f32_16x16x32_bf16 v[112:115], v[172:175], v[180:183], v[112:115]
	v_mfma_f32_16x16x32_bf16 v[96:99], v[172:175], v[196:199], v[96:99]
	v_mfma_f32_16x16x32_bf16 v[96:99], v[176:179], v[200:203], v[96:99]
	v_mfma_f32_16x16x32_bf16 v[100:103], v[168:171], v[200:203], v[100:103]
	v_mfma_f32_16x16x32_bf16 v[100:103], v[160:163], v[196:199], v[100:103]
	v_mfma_f32_16x16x32_bf16 v[84:87], v[160:163], v[204:207], v[84:87]
	v_mfma_f32_16x16x32_bf16 v[84:87], v[168:171], v[208:211], v[84:87]
	v_mfma_f32_16x16x32_bf16 v[80:83], v[176:179], v[208:211], v[80:83]
	v_mfma_f32_16x16x32_bf16 v[80:83], v[172:175], v[204:207], v[80:83]
	v_mfma_f32_16x16x32_bf16 v[64:67], v[172:175], v[212:215], v[64:67]
	v_mfma_f32_16x16x32_bf16 v[64:67], v[176:179], v[216:219], v[64:67]
	v_mfma_f32_16x16x32_bf16 v[68:71], v[168:171], v[216:219], v[68:71]
	v_mfma_f32_16x16x32_bf16 v[68:71], v[160:163], v[212:215], v[68:71]
	s_setprio 0
	s_barrier
	s_add_i32 s66, s52, s40
	s_mov_b32 m0, s66
	ds_read_b128 v[180:183], v194 offset:16384
	ds_read_b128 v[184:187], v194 offset:17408
	ds_read_b128 v[196:199], v194 offset:18432
	ds_read_b128 v[200:203], v194 offset:19456
	ds_read_b128 v[204:207], v194 offset:20480
	ds_read_b128 v[208:211], v194 offset:21504
	ds_read_b128 v[212:215], v194 offset:22528
	ds_read_b128 v[216:219], v194 offset:23552
	global_load_lds_dwordx4 v146, s[36:37]
	s_add_i32 m0, s66, 0x2000
	s_add_u32 s66, s36, 0x200000
	s_addc_u32 s67, s37, 0
	s_add_i32 s68, s53, s40
	global_load_lds_dwordx4 v150, s[36:37]
	s_mov_b32 m0, s68
	s_nop 0
	global_load_lds_dwordx4 v146, s[66:67]
	s_add_i32 m0, s68, 0x2000
	s_nop 0
	global_load_lds_dwordx4 v150, s[66:67]
	s_mov_b32 m0, s41
	s_nop 0
	global_load_lds_dwordx4 v144, s[38:39]
	s_mov_b32 m0, s44
	s_nop 0
	global_load_lds_dwordx4 v148, s[38:39]
	s_waitcnt vmcnt(8)
	s_waitcnt lgkmcnt(0)
	s_barrier
	s_setprio 1
	s_waitcnt lgkmcnt(0)
	v_mfma_f32_16x16x32_bf16 v[60:63], v[128:131], v[180:183], v[60:63]
	v_mfma_f32_16x16x32_bf16 v[60:63], v[132:135], v[184:187], v[60:63]
	v_mfma_f32_16x16x32_bf16 v[56:59], v[140:143], v[184:187], v[56:59]
	v_mfma_f32_16x16x32_bf16 v[56:59], v[136:139], v[180:183], v[56:59]
	v_mfma_f32_16x16x32_bf16 v[40:43], v[136:139], v[196:199], v[40:43]
	v_mfma_f32_16x16x32_bf16 v[40:43], v[140:143], v[200:203], v[40:43]
	v_mfma_f32_16x16x32_bf16 v[44:47], v[132:135], v[200:203], v[44:47]
	v_mfma_f32_16x16x32_bf16 v[44:47], v[128:131], v[196:199], v[44:47]
	v_mfma_f32_16x16x32_bf16 v[28:31], v[128:131], v[204:207], v[28:31]
	v_mfma_f32_16x16x32_bf16 v[28:31], v[132:135], v[208:211], v[28:31]
	v_mfma_f32_16x16x32_bf16 v[24:27], v[140:143], v[208:211], v[24:27]
	v_mfma_f32_16x16x32_bf16 v[24:27], v[136:139], v[204:207], v[24:27]
	v_mfma_f32_16x16x32_bf16 v[8:11], v[136:139], v[212:215], v[8:11]
	v_mfma_f32_16x16x32_bf16 v[8:11], v[140:143], v[216:219], v[8:11]
	v_mfma_f32_16x16x32_bf16 v[12:15], v[132:135], v[216:219], v[12:15]
	v_mfma_f32_16x16x32_bf16 v[12:15], v[128:131], v[212:215], v[12:15]
	s_setprio 0
	s_setprio 1
	v_mfma_f32_16x16x32_bf16 v[52:55], v[160:163], v[180:183], v[52:55]
	v_mfma_f32_16x16x32_bf16 v[52:55], v[168:171], v[184:187], v[52:55]
	v_mfma_f32_16x16x32_bf16 v[48:51], v[176:179], v[184:187], v[48:51]
	v_mfma_f32_16x16x32_bf16 v[48:51], v[172:175], v[180:183], v[48:51]
	v_mfma_f32_16x16x32_bf16 v[32:35], v[172:175], v[196:199], v[32:35]
	v_mfma_f32_16x16x32_bf16 v[32:35], v[176:179], v[200:203], v[32:35]
	v_mfma_f32_16x16x32_bf16 v[36:39], v[168:171], v[200:203], v[36:39]
	v_mfma_f32_16x16x32_bf16 v[36:39], v[160:163], v[196:199], v[36:39]
	v_mfma_f32_16x16x32_bf16 v[20:23], v[160:163], v[204:207], v[20:23]
	v_mfma_f32_16x16x32_bf16 v[20:23], v[168:171], v[208:211], v[20:23]
	v_mfma_f32_16x16x32_bf16 v[16:19], v[176:179], v[208:211], v[16:19]
	v_mfma_f32_16x16x32_bf16 v[16:19], v[172:175], v[204:207], v[16:19]
	v_mfma_f32_16x16x32_bf16 v[0:3], v[172:175], v[212:215], v[0:3]
	v_mfma_f32_16x16x32_bf16 v[0:3], v[176:179], v[216:219], v[0:3]
	v_mfma_f32_16x16x32_bf16 v[4:7], v[168:171], v[216:219], v[4:7]
	v_mfma_f32_16x16x32_bf16 v[4:7], v[160:163], v[212:215], v[4:7]
	s_setprio 0
	s_barrier
; #define PG8_STAGE(bufoff, gbase, voff) do { _Pragma("unroll") for (int _i = 0; _i < 2; ++_i) \
;         __builtin_amdgcn_global_load_lds((const unsigned*)((const char*)(gbase) + (voff)[_i]), (PG8_LAS unsigned*)(lds + (bufoff) + ldsw + _i * 8192), 16, 0, 0); } while (0)
; #define PG8_LDA(dst, b, h) do { _Pragma("unroll") for (int m = 0; m < 4; ++m) _Pragma("unroll") for (int k = 0; k < 2; ++k) dst[m][k] = *(const PG8_LAS bf16x8*)(lds + PG8_SA(b, h) + aoff + m * 2048 + k * 1024); } while (0)
; #define PG8_LDB(dst, b, h) do { _Pragma("unroll") for (int n = 0; n < 2; ++n) _Pragma("unroll") for (int k = 0; k < 2; ++k) dst[n][k] = *(const PG8_LAS bf16x8*)(lds + PG8_SB(b, h) + boff + n * 2048 + k * 1024); } while (0)
; #define PG8_MMA(ai, bj, At, Bt) do { __builtin_amdgcn_s_setprio(1); _Pragma("unroll") for (int m = 0; m < 4; ++m) _Pragma("unroll") for (int n = 0; n < 2; ++n) _Pragma("unroll") for (int k = 0; k < 2; ++k) \
;         acc[ai][bj][m][n] = __builtin_amdgcn_mfma_f32_16x16x32_bf16(Bt[n][k], At[m][k], acc[ai][bj][m][n], 0, 0, 0); __builtin_amdgcn_s_setprio(0); } while (0)
; #define PG8_WAIT_V(n) asm volatile("s_waitcnt vmcnt(" #n ")" ::: "memory")
; #define PG8_WAIT_L(n) asm volatile("s_waitcnt lgkmcnt(" #n ")" ::: "memory")
; #define PG8_BAR __builtin_amdgcn_s_barrier()
; #define PG8_SCHED __builtin_amdgcn_sched_barrier(0)
; template <class Epi, class Sched, bool ALIGN_EPI = false, bool SP2 = false>
; __device__ __forceinline__ void gemm_phase(PG8_LAS unsigned char* lds, const Gemm g, const Sched& S, const Epi& E) {
;     ...
;             PG8_LDB(B0, 1, 0); PG8_LDB(B1, 1, 1); PG8_SCHED; PG8_LDA(At, 1, 0); PG8_STAGE(PG8_SA(0, 1), a2 + hstepA, voffA);
;             PG8_WAIT_V(8); PG8_WAIT_L(0); PG8_BAR; PG8_MMA(0, 0, At, B0); PG8_MMA(0, 1, At, B1); PG8_BAR; PG8_SCHED;
;             PG8_LDA(At, 1, 1); PG8_STAGE(PG8_SB(1, 0), b3, voffB); PG8_STAGE(PG8_SB(1, 1), b3 + hstepB, voffB); PG8_STAGE(PG8_SA(1, 0), a3, voffA);
;             PG8_WAIT_V(8); PG8_WAIT_L(0); PG8_BAR; PG8_MMA(1, 0, At, B0); PG8_MMA(1, 1, At, B1); PG8_BAR; PG8_SCHED;
	s_add_i32 s66, 0, 0x18000
	s_add_i32 s67, 0, 0x1c000
	v_add_u32_e32 v140, s66, v190
	v_add_u32_e32 v176, s67, v190
	ds_read_b128 v[128:131], v140
	ds_read_b128 v[132:135], v140 offset:1024
	ds_read_b128 v[136:139], v140 offset:2048
	ds_read_b128 v[140:143], v140 offset:3072
	ds_read_b128 v[160:163], v176
	ds_read_b128 v[168:171], v176 offset:1024
	ds_read_b128 v[172:175], v176 offset:2048
	ds_read_b128 v[176:179], v176 offset:3072
	s_add_u32 s38, s38, 0x490000
	s_addc_u32 s39, s39, 0
	s_mov_b32 m0, s45
	ds_read_b128 v[180:183], v194 offset:32768
	ds_read_b128 v[184:187], v194 offset:33792
	ds_read_b128 v[196:199], v194 offset:34816
	ds_read_b128 v[200:203], v194 offset:35840
	ds_read_b128 v[204:207], v194 offset:36864
	ds_read_b128 v[208:211], v194 offset:37888
	ds_read_b128 v[212:215], v194 offset:38912
	ds_read_b128 v[216:219], v194 offset:39936
	global_load_lds_dwordx4 v144, s[38:39]
	s_mov_b32 m0, s46
	s_nop 0
	global_load_lds_dwordx4 v148, s[38:39]
	s_waitcnt vmcnt(8)
	s_waitcnt lgkmcnt(0)
	s_barrier
	s_setprio 1
	s_waitcnt lgkmcnt(0)
	v_mfma_f32_16x16x32_bf16 v[124:127], v[128:131], v[180:183], v[124:127]
	v_mfma_f32_16x16x32_bf16 v[124:127], v[132:135], v[184:187], v[124:127]
	v_mfma_f32_16x16x32_bf16 v[120:123], v[140:143], v[184:187], v[120:123]
	v_mfma_f32_16x16x32_bf16 v[120:123], v[136:139], v[180:183], v[120:123]
	v_mfma_f32_16x16x32_bf16 v[104:107], v[136:139], v[196:199], v[104:107]
	v_mfma_f32_16x16x32_bf16 v[104:107], v[140:143], v[200:203], v[104:107]
	v_mfma_f32_16x16x32_bf16 v[108:111], v[132:135], v[200:203], v[108:111]
	v_mfma_f32_16x16x32_bf16 v[108:111], v[128:131], v[196:199], v[108:111]
	v_mfma_f32_16x16x32_bf16 v[92:95], v[128:131], v[204:207], v[92:95]
	v_mfma_f32_16x16x32_bf16 v[92:95], v[132:135], v[208:211], v[92:95]
	v_mfma_f32_16x16x32_bf16 v[88:91], v[140:143], v[208:211], v[88:91]
	v_mfma_f32_16x16x32_bf16 v[88:91], v[136:139], v[204:207], v[88:91]
	v_mfma_f32_16x16x32_bf16 v[72:75], v[136:139], v[212:215], v[72:75]
	v_mfma_f32_16x16x32_bf16 v[72:75], v[140:143], v[216:219], v[72:75]
	v_mfma_f32_16x16x32_bf16 v[76:79], v[132:135], v[216:219], v[76:79]
	v_mfma_f32_16x16x32_bf16 v[76:79], v[128:131], v[212:215], v[76:79]
	s_setprio 0
	s_setprio 1
	v_mfma_f32_16x16x32_bf16 v[116:119], v[160:163], v[180:183], v[116:119]
	v_mfma_f32_16x16x32_bf16 v[116:119], v[168:171], v[184:187], v[116:119]
	v_mfma_f32_16x16x32_bf16 v[112:115], v[176:179], v[184:187], v[112:115]
	v_mfma_f32_16x16x32_bf16 v[112:115], v[172:175], v[180:183], v[112:115]
	v_mfma_f32_16x16x32_bf16 v[96:99], v[172:175], v[196:199], v[96:99]
	v_mfma_f32_16x16x32_bf16 v[96:99], v[176:179], v[200:203], v[96:99]
	v_mfma_f32_16x16x32_bf16 v[100:103], v[168:171], v[200:203], v[100:103]
	v_mfma_f32_16x16x32_bf16 v[100:103], v[160:163], v[196:199], v[100:103]
	v_mfma_f32_16x16x32_bf16 v[84:87], v[160:163], v[204:207], v[84:87]
	v_mfma_f32_16x16x32_bf16 v[84:87], v[168:171], v[208:211], v[84:87]
	v_mfma_f32_16x16x32_bf16 v[80:83], v[176:179], v[208:211], v[80:83]
	v_mfma_f32_16x16x32_bf16 v[80:83], v[172:175], v[204:207], v[80:83]
	v_mfma_f32_16x16x32_bf16 v[64:67], v[172:175], v[212:215], v[64:67]
	v_mfma_f32_16x16x32_bf16 v[64:67], v[176:179], v[216:219], v[64:67]
	v_mfma_f32_16x16x32_bf16 v[68:71], v[168:171], v[216:219], v[68:71]
	v_mfma_f32_16x16x32_bf16 v[68:71], v[160:163], v[212:215], v[68:71]
	s_setprio 0
	s_barrier
	s_add_i32 s38, s66, s40
	s_mov_b32 m0, s38
	ds_read_b128 v[180:183], v194 offset:49152
	ds_read_b128 v[184:187], v194 offset:50176
	ds_read_b128 v[196:199], v194 offset:51200
	ds_read_b128 v[200:203], v194 offset:52224
	ds_read_b128 v[204:207], v194 offset:53248
	ds_read_b128 v[208:211], v194 offset:54272
	ds_read_b128 v[212:215], v194 offset:55296
	ds_read_b128 v[216:219], v194 offset:56320
	global_load_lds_dwordx4 v146, s[98:99]
	s_add_i32 m0, s38, 0x2000
	s_add_u32 s36, s36, 0x200080
	s_addc_u32 s37, s37, 0
	s_add_i32 s38, s67, s40
	global_load_lds_dwordx4 v150, s[98:99]
	s_mov_b32 m0, s38
	s_nop 0
	global_load_lds_dwordx4 v146, s[36:37]
	s_add_i32 m0, s38, 0x2000
	s_nop 0
	global_load_lds_dwordx4 v150, s[36:37]
	s_mov_b32 m0, s47
	s_nop 0
	global_load_lds_dwordx4 v144, s[100:101]
	s_mov_b32 m0, s48
	s_nop 0
	global_load_lds_dwordx4 v148, s[100:101]
	s_waitcnt vmcnt(8)
	s_waitcnt lgkmcnt(0)
	s_barrier
	s_setprio 1
	s_waitcnt lgkmcnt(0)
	v_mfma_f32_16x16x32_bf16 v[60:63], v[128:131], v[180:183], v[60:63]
	v_mfma_f32_16x16x32_bf16 v[60:63], v[132:135], v[184:187], v[60:63]
	v_mfma_f32_16x16x32_bf16 v[56:59], v[140:143], v[184:187], v[56:59]
	v_mfma_f32_16x16x32_bf16 v[56:59], v[136:139], v[180:183], v[56:59]
	v_mfma_f32_16x16x32_bf16 v[40:43], v[136:139], v[196:199], v[40:43]
	v_mfma_f32_16x16x32_bf16 v[40:43], v[140:143], v[200:203], v[40:43]
	v_mfma_f32_16x16x32_bf16 v[44:47], v[132:135], v[200:203], v[44:47]
	v_mfma_f32_16x16x32_bf16 v[44:47], v[128:131], v[196:199], v[44:47]
	v_mfma_f32_16x16x32_bf16 v[28:31], v[128:131], v[204:207], v[28:31]
	v_mfma_f32_16x16x32_bf16 v[28:31], v[132:135], v[208:211], v[28:31]
	v_mfma_f32_16x16x32_bf16 v[24:27], v[140:143], v[208:211], v[24:27]
	v_mfma_f32_16x16x32_bf16 v[24:27], v[136:139], v[204:207], v[24:27]
	v_mfma_f32_16x16x32_bf16 v[8:11], v[136:139], v[212:215], v[8:11]
	v_mfma_f32_16x16x32_bf16 v[8:11], v[140:143], v[216:219], v[8:11]
	v_mfma_f32_16x16x32_bf16 v[12:15], v[132:135], v[216:219], v[12:15]
	v_mfma_f32_16x16x32_bf16 v[12:15], v[128:131], v[212:215], v[12:15]
	s_setprio 0
	s_setprio 1
	v_mfma_f32_16x16x32_bf16 v[52:55], v[160:163], v[180:183], v[52:55]
	v_mfma_f32_16x16x32_bf16 v[52:55], v[168:171], v[184:187], v[52:55]
	v_mfma_f32_16x16x32_bf16 v[48:51], v[176:179], v[184:187], v[48:51]
	v_mfma_f32_16x16x32_bf16 v[48:51], v[172:175], v[180:183], v[48:51]
	v_mfma_f32_16x16x32_bf16 v[32:35], v[172:175], v[196:199], v[32:35]
	v_mfma_f32_16x16x32_bf16 v[32:35], v[176:179], v[200:203], v[32:35]
	v_mfma_f32_16x16x32_bf16 v[36:39], v[168:171], v[200:203], v[36:39]
	v_mfma_f32_16x16x32_bf16 v[36:39], v[160:163], v[196:199], v[36:39]
	v_mfma_f32_16x16x32_bf16 v[20:23], v[160:163], v[204:207], v[20:23]
	v_mfma_f32_16x16x32_bf16 v[20:23], v[168:171], v[208:211], v[20:23]
	v_mfma_f32_16x16x32_bf16 v[16:19], v[176:179], v[208:211], v[16:19]
	v_mfma_f32_16x16x32_bf16 v[16:19], v[172:175], v[204:207], v[16:19]
	v_mfma_f32_16x16x32_bf16 v[0:3], v[172:175], v[212:215], v[0:3]
	v_mfma_f32_16x16x32_bf16 v[0:3], v[176:179], v[216:219], v[0:3]
	v_mfma_f32_16x16x32_bf16 v[4:7], v[168:171], v[216:219], v[4:7]
	v_mfma_f32_16x16x32_bf16 v[4:7], v[160:163], v[212:215], v[4:7]
	s_setprio 0
	s_barrier
	s_add_i32 s65, s65, 2
	s_add_u32 s6, s6, 0x100
	s_addc_u32 s7, s7, 0
	s_add_u32 s63, s63, 0x100
	s_addc_u32 s64, s64, 0
	s_cmpk_gt_u32 s65, 0x7d
	s_cbranch_scc0 .LBB0_882
	s_and_b64 vcc, exec, s[22:23]
	s_cbranch_vccz .LBB0_885
	s_barrier

; __global__ void __launch_bounds__(512, 2) fwd(Args args) {
	.amdhsa_kernel _Z3fwd4Args
		.amdhsa_group_segment_fixed_size 0
		.amdhsa_private_segment_fixed_size 0
		.amdhsa_kernarg_size 464
		.amdhsa_user_sgpr_count 2
		.amdhsa_user_sgpr_dispatch_ptr 0
		.amdhsa_user_sgpr_queue_ptr 0
		.amdhsa_user_sgpr_kernarg_segment_ptr 1
		.amdhsa_user_sgpr_dispatch_id 0
		.amdhsa_user_sgpr_kernarg_preload_length 0
		.amdhsa_user_sgpr_kernarg_preload_offset 0
		.amdhsa_user_sgpr_private_segment_size 0
		.amdhsa_uses_dynamic_stack 0
		.amdhsa_enable_private_segment 0
		.amdhsa_system_sgpr_workgroup_id_x 1
		.amdhsa_system_sgpr_workgroup_id_y 0
		.amdhsa_system_sgpr_workgroup_id_z 0
		.amdhsa_system_sgpr_workgroup_info 0
		.amdhsa_system_vgpr_workitem_id 0
		.amdhsa_next_free_vgpr 254
		.amdhsa_next_free_sgpr 102
		.amdhsa_accum_offset 256
		.amdhsa_reserve_vcc 1
		.amdhsa_float_round_mode_32 0
		.amdhsa_float_round_mode_16_64 0
		.amdhsa_float_denorm_mode_32 3
		.amdhsa_float_denorm_mode_16_64 3
		.amdhsa_dx10_clamp 1
		.amdhsa_ieee_mode 1
		.amdhsa_fp16_overflow 0
		.amdhsa_tg_split 0
		.amdhsa_exception_fp_ieee_invalid_op 0
		.amdhsa_exception_fp_denorm_src 0
		.amdhsa_exception_fp_ieee_div_zero 0
		.amdhsa_exception_fp_ieee_overflow 0
		.amdhsa_exception_fp_ieee_underflow 0
		.amdhsa_exception_fp_ieee_inexact 0
		.amdhsa_exception_int_div_zero 0
	.end_amdhsa_kernel

; __global__ void __launch_bounds__(512, 2) fwd(Args args) {
amdhsa.kernels:
  - .agpr_count:     0
    .args:
      - .offset:         0
        .size:           208
        .value_kind:     by_value
      - .offset:         208
        .size:           4
        .value_kind:     hidden_block_count_x
      - .offset:         212
        .size:           4
        .value_kind:     hidden_block_count_y
      - .offset:         216
        .size:           4
        .value_kind:     hidden_block_count_z
      - .offset:         220
        .size:           2
        .value_kind:     hidden_group_size_x
      - .offset:         222
        .size:           2
        .value_kind:     hidden_group_size_y
      - .offset:         224
        .size:           2
        .value_kind:     hidden_group_size_z
      - .offset:         226
        .size:           2
        .value_kind:     hidden_remainder_x
      - .offset:         228
        .size:           2
        .value_kind:     hidden_remainder_y
      - .offset:         230
        .size:           2
        .value_kind:     hidden_remainder_z
      - .offset:         248
        .size:           8
        .value_kind:     hidden_global_offset_x
      - .offset:         256
        .size:           8
        .value_kind:     hidden_global_offset_y
      - .offset:         264
        .size:           8
        .value_kind:     hidden_global_offset_z
      - .offset:         272
        .size:           2
        .value_kind:     hidden_grid_dims
      - .offset:         328
        .size:           4
        .value_kind:     hidden_dynamic_lds_size
    .group_segment_fixed_size: 0
    .kernarg_segment_align: 8
    .kernarg_segment_size: 464
    .language:       OpenCL C
    .language_version:
      - 2
      - 0
    .max_flat_workgroup_size: 512
    .name:           _Z3fwd4Args
    .private_segment_fixed_size: 0
    .sgpr_count:     108
    .sgpr_spill_count: 80
    .symbol:         _Z3fwd4Args.kd
    .uniform_work_group_size: 1
    .uses_dynamic_stack: false
    .vgpr_count:     254
    .vgpr_spill_count: 0
    .wavefront_size: 64
